# P3: u loads / out stores as 2 x dwordx4 per lane with v_permlane32_swap re-pairing (half the load/store instructions, 32-byte contiguous per lane)
# speedup vs baseline: 1.0038x; 1.0038x over previous
; __device__ __forceinline__ unsigned pk2(float lo, float hi) { f32x2_t v = {lo, hi}; bf16x2_t b = __builtin_convertvector(v, bf16x2_t); return __builtin_bit_cast(unsigned, b); }
; #define tid (otid())
; __global__ void __launch_bounds__(512, 2) mega_fwd(Args a) {
;     ...
;         const int r32 = lane & 31, hi = lane >> 5, iblk = wave >> 1, dblk = wave & 1;
;         const int jt = tid >> 2, qd = tid & 3;
;         u32x4 r0, r1; f32x4 lgv[4], lbv[4];
;         const int ustep = (G == 256) ? 1 : G;
;         const int jx = vcu & 31;
;         const int u0 = (G == 256) ? (256 * (vcu >> 5) + (jx < 16 ? 7 * jx : 112 + 9 * (jx - 16))) : vcu;
;         const int ucnt = (G == 256) ? (bx < 128 ? 7 : 9) : (vcu < 2048 ? (2047 - vcu) / G + 1 : 0);
;         if (ucnt > 0) { const bf16_t* vp = Z + ((size_t)(u0 >> 3) * 128 + jt) * NZ + 1024 + (u0 & 7) * 64 + 16 * qd; r0 = *(const u32x4*)vp; r1 = *(const u32x4*)(vp + 8);
; #pragma unroll
;             for (int e4 = 0; e4 < 4; ++e4) { lgv[e4] = *(const f32x4*)(KA->gm_ln_g + (u0 & 7) * 64 + 16 * qd + 4 * e4); lbv[e4] = *(const f32x4*)(KA->gm_ln_b + (u0 & 7) * 64 + 16 * qd + 4 * e4); } }
;         for (int ui = 0, u = u0; ui < ucnt; ++ui, u += ustep) {
;             const int blk = u >> 3, h = u & 7; const size_t t0 = (size_t)blk * 128;
;             {
;                 float xv[16];
;                 xv[0] = bf_lo(r0.x); xv[1] = bf_hi(r0.x); xv[2] = bf_lo(r0.y); xv[3] = bf_hi(r0.y); xv[4] = bf_lo(r0.z); xv[5] = bf_hi(r0.z); xv[6] = bf_lo(r0.w); xv[7] = bf_hi(r0.w);
;                 xv[8] = bf_lo(r1.x); xv[9] = bf_hi(r1.x); xv[10] = bf_lo(r1.y); xv[11] = bf_hi(r1.y); xv[12] = bf_lo(r1.z); xv[13] = bf_hi(r1.z); xv[14] = bf_lo(r1.w); xv[15] = bf_hi(r1.w);
;                 float sm = 0.f;
; #pragma unroll
;                 for (int e = 0; e < 16; ++e) sm += xv[e];
;                 sm += __shfl_xor(sm, 1); sm += __shfl_xor(sm, 2);
;                 const float mu = sm * (1.0f / 64.0f); float q = 0.f;
; #pragma unroll
;                 for (int e = 0; e < 16; ++e) { xv[e] -= mu; q += xv[e] * xv[e]; }
;                 q += __shfl_xor(q, 1); q += __shfl_xor(q, 2);
;                 const float rstd = rsqrtf(q * (1.0f / 64.0f) + EPS);
; #pragma unroll
;                 for (int e = 0; e < 16; ++e) { const float y = xv[e] * rstd * lgv[e >> 2][e & 3] + lbv[e >> 2][e & 3]; VLT[(16 * qd + e) * VLP + jt] = (bf16_t)(pk2(y, 0.f) & 0xffffu); }
.Lp3r_entry:
	s_and_b32 s10, s54, 31
	s_and_b32 s22, s10, 7
	s_lshr_b32 s11, s10, 3
	s_mul_i32 s12, s11, 7
	s_mul_i32 s13, s11, 9
	s_sub_u32 s13, s13, 4
	s_cmp_lt_u32 s11, 2
	s_cselect_b32 s12, s12, s13
	s_cselect_b32 s18, 7, 9
	s_and_b32 s39, s39, 0xffffff00
	s_lshr_b32 s39, s39, 3
	s_add_u32 s21, s39, s12
	s_mul_i32 s24, s21, 0x60000
	s_lshl_b32 s25, s22, 7
	s_add_u32 s24, s24, s25
	s_add_u32 s24, s24, 0x6000000
	s_add_u32 s26, s8, s24
	s_addc_u32 s27, s9, 0
	s_lshl_b32 s24, s21, 18
	s_add_u32 s24, s24, s25
	s_add_u32 s24, s24, 0x14a00000
	s_add_u32 s48, s8, s24
	s_addc_u32 s49, s9, 0
	s_lshl_b32 s24, s22, 15
	s_add_u32 s24, s24, 0x180000
	s_add_u32 s36, s8, s24
	s_addc_u32 s37, s9, 0
	s_lshl_b32 s24, s22, 9
	s_add_u32 s46, s16, s24
	s_addc_u32 s47, s17, 0
	s_lshl_b32 s24, s22, 8
	s_add_u32 s50, s40, s24
	s_addc_u32 s51, s41, 0
	s_add_u32 s52, s42, s24
	s_addc_u32 s53, s43, 0
	v_lshlrev_b32_e32 v109, 6, v104
	v_mul_u32_u24_e32 v110, 24, v107
	v_add_u32_e32 v233, v113, v110
	v_add_u32_e32 v234, v116, v110
	global_load_dwordx4 v[120:123], v114, s[36:37]
	global_load_dwordx4 v[124:127], v114, s[36:37] offset:32
	global_load_dwordx4 v[128:131], v114, s[36:37] offset:64
	global_load_dwordx4 v[132:135], v114, s[36:37] offset:96
	global_load_dwordx4 v[136:139], v114, s[36:37] offset:128
	global_load_dwordx4 v[140:143], v114, s[36:37] offset:160
	global_load_dwordx4 v[144:147], v114, s[36:37] offset:192
	global_load_dwordx4 v[148:151], v114, s[36:37] offset:224
	global_load_dword v32, v115, s[46:47]
	global_load_dwordx4 v[152:155], v109, s[50:51]
	global_load_dwordx4 v[156:159], v109, s[50:51] offset:16
	global_load_dwordx4 v[160:163], v109, s[50:51] offset:32
	global_load_dwordx4 v[164:167], v109, s[50:51] offset:48
	global_load_dwordx4 v[168:171], v109, s[52:53]
	global_load_dwordx4 v[172:175], v109, s[52:53] offset:16
	global_load_dwordx4 v[176:179], v109, s[52:53] offset:32
	global_load_dwordx4 v[180:183], v109, s[52:53] offset:48
	s_mov_b32 s45, 0
	global_load_dwordx4 v[16:19], v112, s[26:27]
	global_load_dwordx4 v[20:23], v112, s[26:27] offset:16
	global_load_dwordx4 v[24:27], v233, s[26:27]
	global_load_dwordx4 v[28:31], v233, s[26:27] offset:16
	s_add_u32 s26, s26, 0x60000
	s_addc_u32 s27, s27, 0
	s_cmp_lt_u32 s18, 2
	s_cbranch_scc1 .Lp3r_tail0
	global_load_dwordx4 v[40:43], v112, s[26:27]
	global_load_dwordx4 v[44:47], v112, s[26:27] offset:16
	global_load_dwordx4 v[48:51], v233, s[26:27]
	global_load_dwordx4 v[52:55], v233, s[26:27] offset:16
	s_add_u32 s26, s26, 0x60000
	s_addc_u32 s27, s27, 0
.Lp3r_body0:
	s_add_u32 s44, s45, 2
	s_cmp_lt_u32 s44, s18
	s_cbranch_scc0 .Lp3r_tail0
	global_load_dwordx4 v[56:59], v112, s[26:27]
	global_load_dwordx4 v[60:63], v112, s[26:27] offset:16
	global_load_dwordx4 v[64:67], v233, s[26:27]
	global_load_dwordx4 v[68:71], v233, s[26:27] offset:16
	s_add_u32 s26, s26, 0x60000
	s_addc_u32 s27, s27, 0
	s_waitcnt vmcnt(11)
	v_lshlrev_b32_e32 v200, 16, v16
	v_and_b32_e32 v201, s38, v16
	v_lshlrev_b32_e32 v202, 16, v17
	v_and_b32_e32 v203, s38, v17
	v_lshlrev_b32_e32 v204, 16, v18
	v_and_b32_e32 v205, s38, v18
	v_lshlrev_b32_e32 v206, 16, v19
	v_and_b32_e32 v207, s38, v19
	s_waitcnt vmcnt(10)
	v_lshlrev_b32_e32 v208, 16, v20
	v_and_b32_e32 v209, s38, v20
	v_lshlrev_b32_e32 v210, 16, v21
	v_and_b32_e32 v211, s38, v21
	v_lshlrev_b32_e32 v212, 16, v22
	v_and_b32_e32 v213, s38, v22
	v_lshlrev_b32_e32 v214, 16, v23
	v_and_b32_e32 v215, s38, v23
	v_pk_add_f32 v[216:217], v[200:201], v[202:203]
	v_pk_add_f32 v[218:219], v[204:205], v[206:207]
	v_pk_add_f32 v[220:221], v[208:209], v[210:211]
	v_pk_add_f32 v[222:223], v[212:213], v[214:215]
	v_pk_add_f32 v[216:217], v[216:217], v[218:219]
	v_pk_add_f32 v[220:221], v[220:221], v[222:223]
	v_pk_add_f32 v[216:217], v[216:217], v[220:221]
	v_add_f32_e32 v216, v216, v217
	s_nop 1
	v_add_f32_dpp v217, v216, v216 quad_perm:[1,0,3,2] row_mask:0xf bank_mask:0xf
	s_nop 1
	v_add_f32_dpp v216, v217, v217 quad_perm:[2,3,0,1] row_mask:0xf bank_mask:0xf
	v_mul_f32_e32 v216, 0xbc800000, v216
	v_pk_add_f32 v[200:201], v[200:201], v[216:217] op_sel_hi:[1,0]
	v_pk_add_f32 v[202:203], v[202:203], v[216:217] op_sel_hi:[1,0]
	v_pk_add_f32 v[204:205], v[204:205], v[216:217] op_sel_hi:[1,0]
	v_pk_add_f32 v[206:207], v[206:207], v[216:217] op_sel_hi:[1,0]
	v_pk_add_f32 v[208:209], v[208:209], v[216:217] op_sel_hi:[1,0]
	v_pk_add_f32 v[210:211], v[210:211], v[216:217] op_sel_hi:[1,0]
	v_pk_add_f32 v[212:213], v[212:213], v[216:217] op_sel_hi:[1,0]
	v_pk_add_f32 v[214:215], v[214:215], v[216:217] op_sel_hi:[1,0]
	v_pk_mul_f32 v[218:219], v[200:201], v[200:201]
	v_pk_mul_f32 v[220:221], v[202:203], v[202:203]
	v_pk_fma_f32 v[218:219], v[204:205], v[204:205], v[218:219]
	v_pk_fma_f32 v[220:221], v[206:207], v[206:207], v[220:221]
	v_pk_fma_f32 v[218:219], v[208:209], v[208:209], v[218:219]
	v_pk_fma_f32 v[220:221], v[210:211], v[210:211], v[220:221]
	v_pk_fma_f32 v[218:219], v[212:213], v[212:213], v[218:219]
	v_pk_fma_f32 v[220:221], v[214:215], v[214:215], v[220:221]
	v_pk_add_f32 v[218:219], v[218:219], v[220:221]
	v_add_f32_e32 v218, v218, v219
	s_nop 1
	v_add_f32_dpp v219, v218, v218 quad_perm:[1,0,3,2] row_mask:0xf bank_mask:0xf
	s_nop 1
	v_add_f32_dpp v218, v219, v219 quad_perm:[2,3,0,1] row_mask:0xf bank_mask:0xf
	v_fmamk_f32 v218, v218, 0x3c800000, v111
	v_rsq_f32_e32 v218, v218
	s_nop 0
	v_pk_mul_f32 v[200:201], v[200:201], v[218:219] op_sel_hi:[1,0]
	v_pk_mul_f32 v[202:203], v[202:203], v[218:219] op_sel_hi:[1,0]
	v_pk_mul_f32 v[204:205], v[204:205], v[218:219] op_sel_hi:[1,0]
	v_pk_mul_f32 v[206:207], v[206:207], v[218:219] op_sel_hi:[1,0]
	v_pk_mul_f32 v[208:209], v[208:209], v[218:219] op_sel_hi:[1,0]
; #define LAS __attribute__((address_space(3)))
; __global__ void __launch_bounds__(512, 2) mega_fwd(Args a) {
;     ...
;                 const float rstd = rsqrtf(q * (1.0f / 64.0f) + EPS);
; #pragma unroll
;                 for (int e = 0; e < 16; ++e) { const float y = xv[e] * rstd * lgv[e >> 2][e & 3] + lbv[e >> 2][e & 3]; VLT[(16 * qd + e) * VLP + jt] = (bf16_t)(pk2(y, 0.f) & 0xffffu); }
;             }
;             const int un = u + ustep;
;             if (ui + 1 < ucnt) { const bf16_t* vp = Z + ((size_t)(un >> 3) * 128 + jt) * NZ + 1024 + (un & 7) * 64 + 16 * qd; r0 = *(const u32x4*)vp; r1 = *(const u32x4*)(vp + 8);
; #pragma unroll
;                 for (int e4 = 0; e4 < 4; ++e4) { lgv[e4] = *(const f32x4*)(KA->gm_ln_g + (un & 7) * 64 + 16 * qd + 4 * e4); lbv[e4] = *(const f32x4*)(KA->gm_ln_b + (un & 7) * 64 + 16 * qd + 4 * e4); } }
;             const int itok = 32 * iblk + r32;
;             const bf16_t* up = Z + (t0 + itok) * NZ + 512 + h * 64 + 32 * dblk + 4 * hi;
;             u32x2 uu[4];
; #pragma unroll
;             for (int g = 0; g < 4; ++g) uu[g] = *(const u32x2*)(up + 8 * g);
;             const float bsp = KA->b_spatial[h * 128 + itok];
;             bf16x8 wf[8];
;             { const bf16_t* wp = WSP + ((size_t)h * 128 + itok) * 128 + 8 * hi;
; #pragma unroll
;               for (int s = 0; s < 8; ++s) if (s < 4 || iblk >= 2) wf[s] = *(const bf16x8*)(wp + 16 * s); }
;             __syncthreads();
;             {
;                 f32x16 acc;
; #pragma unroll
;                 for (int r = 0; r < 16; ++r) acc[r] = 0.f;
;                 const LAS bf16_t* vl = VLT + (32 * dblk + r32) * VLP + 8 * hi;
; #pragma unroll
;                 for (int s = 0; s < 8; ++s) if (s < 4 || iblk >= 2) {
;                     const bf16x8 vf = *(const LAS bf16x8*)(vl + 16 * s);
;                     acc = __builtin_amdgcn_mfma_f32_32x32x16_bf16(vf, wf[s], acc, 0, 0, 0);
;                 }
;                 bf16_t* op = AO + (t0 + itok) * DM + 512 + h * 64 + 32 * dblk + 4 * hi;
; #pragma unroll
;                 for (int g = 0; g < 4; ++g) {
;                     u32x2 w; w.x = pk2(bf_lo(uu[g].x) * (acc[4 * g] + bsp), bf_hi(uu[g].x) * (acc[4 * g + 1] + bsp)); w.y = pk2(bf_lo(uu[g].y) * (acc[4 * g + 2] + bsp), bf_hi(uu[g].y) * (acc[4 * g + 3] + bsp));
;                     *(u32x2*)(op + 8 * g) = w;
;                 }
	v_pk_mul_f32 v[210:211], v[210:211], v[218:219] op_sel_hi:[1,0]
	v_pk_mul_f32 v[212:213], v[212:213], v[218:219] op_sel_hi:[1,0]
	v_pk_mul_f32 v[214:215], v[214:215], v[218:219] op_sel_hi:[1,0]
	v_pk_fma_f32 v[200:201], v[200:201], v[152:153], v[168:169]
	v_pk_fma_f32 v[202:203], v[202:203], v[154:155], v[170:171]
	v_pk_fma_f32 v[204:205], v[204:205], v[156:157], v[172:173]
	v_pk_fma_f32 v[206:207], v[206:207], v[158:159], v[174:175]
	v_pk_fma_f32 v[208:209], v[208:209], v[160:161], v[176:177]
	v_pk_fma_f32 v[210:211], v[210:211], v[162:163], v[178:179]
	v_pk_fma_f32 v[212:213], v[212:213], v[164:165], v[180:181]
	v_pk_fma_f32 v[214:215], v[214:215], v[166:167], v[182:183]
	v_cvt_pk_bf16_f32 v224, v200, v201
	v_cvt_pk_bf16_f32 v225, v202, v203
	v_cvt_pk_bf16_f32 v226, v204, v205
	v_cvt_pk_bf16_f32 v227, v206, v207
	v_cvt_pk_bf16_f32 v228, v208, v209
	v_cvt_pk_bf16_f32 v229, v210, v211
	v_cvt_pk_bf16_f32 v230, v212, v213
	v_cvt_pk_bf16_f32 v231, v214, v215
	ds_write_b16 v117, v224 offset:0
	ds_write_b16_d16_hi v117, v224 offset:272
	ds_write_b16 v117, v225 offset:544
	ds_write_b16_d16_hi v117, v225 offset:816
	ds_write_b16 v117, v226 offset:1088
	ds_write_b16_d16_hi v117, v226 offset:1360
	ds_write_b16 v117, v227 offset:1632
	ds_write_b16_d16_hi v117, v227 offset:1904
	ds_write_b16 v117, v228 offset:2176
	ds_write_b16_d16_hi v117, v228 offset:2448
	ds_write_b16 v117, v229 offset:2720
	ds_write_b16_d16_hi v117, v229 offset:2992
	ds_write_b16 v117, v230 offset:3264
	ds_write_b16_d16_hi v117, v230 offset:3536
	ds_write_b16 v117, v231 offset:3808
	ds_write_b16_d16_hi v117, v231 offset:4080
	s_waitcnt lgkmcnt(0)
	s_barrier
	ds_read_b128 v[88:91], v118 offset:0
	ds_read_b128 v[92:95], v118 offset:32
	ds_read_b128 v[96:99], v118 offset:64
	ds_read_b128 v[100:103], v118 offset:96
	s_waitcnt lgkmcnt(3)
	v_mfma_f32_32x32x16_bf16 v[0:15], v[88:91], v[120:123], 0
	s_waitcnt lgkmcnt(2)
	v_mfma_f32_32x32x16_bf16 v[0:15], v[92:95], v[124:127], v[0:15]
	s_waitcnt lgkmcnt(1)
	v_mfma_f32_32x32x16_bf16 v[0:15], v[96:99], v[128:131], v[0:15]
	s_waitcnt lgkmcnt(0)
	v_mfma_f32_32x32x16_bf16 v[0:15], v[100:103], v[132:135], v[0:15]
	s_cmp_lt_u32 s20, 0x100
	s_cbranch_scc1 .Lp3r_half0
	ds_read_b128 v[88:91], v118 offset:128
	ds_read_b128 v[92:95], v118 offset:160
	ds_read_b128 v[96:99], v118 offset:192
	ds_read_b128 v[100:103], v118 offset:224
	s_waitcnt lgkmcnt(3)
	v_mfma_f32_32x32x16_bf16 v[0:15], v[88:91], v[136:139], v[0:15]
	s_waitcnt lgkmcnt(2)
	v_mfma_f32_32x32x16_bf16 v[0:15], v[92:95], v[140:143], v[0:15]
	s_waitcnt lgkmcnt(1)
	v_mfma_f32_32x32x16_bf16 v[0:15], v[96:99], v[144:147], v[0:15]
	s_waitcnt lgkmcnt(0)
	v_mfma_f32_32x32x16_bf16 v[0:15], v[100:103], v[148:151], v[0:15]
.Lp3r_half0:
	s_waitcnt vmcnt(8)
	v_permlane32_swap_b32_e32 v24, v26
	v_permlane32_swap_b32_e32 v25, v27
	v_permlane32_swap_b32_e32 v28, v30
	v_permlane32_swap_b32_e32 v29, v31
	s_nop 0
	v_lshlrev_b32_e32 v200, 16, v24
	v_and_b32_e32 v201, s38, v24
	v_lshlrev_b32_e32 v202, 16, v25
	v_and_b32_e32 v203, s38, v25
	v_lshlrev_b32_e32 v204, 16, v28
	v_and_b32_e32 v205, s38, v28
	v_lshlrev_b32_e32 v206, 16, v29
	v_and_b32_e32 v207, s38, v29
	v_lshlrev_b32_e32 v208, 16, v26
	v_and_b32_e32 v209, s38, v26
	v_lshlrev_b32_e32 v210, 16, v27
	v_and_b32_e32 v211, s38, v27
	v_lshlrev_b32_e32 v212, 16, v30
	v_and_b32_e32 v213, s38, v30
	v_lshlrev_b32_e32 v214, 16, v31
	v_and_b32_e32 v215, s38, v31
	s_nop 7
	v_pk_add_f32 v[0:1], v[0:1], v[32:33] op_sel_hi:[1,0]
	v_pk_add_f32 v[2:3], v[2:3], v[32:33] op_sel_hi:[1,0]
	v_pk_add_f32 v[4:5], v[4:5], v[32:33] op_sel_hi:[1,0]
	v_pk_add_f32 v[6:7], v[6:7], v[32:33] op_sel_hi:[1,0]
	v_pk_add_f32 v[8:9], v[8:9], v[32:33] op_sel_hi:[1,0]
	v_pk_add_f32 v[10:11], v[10:11], v[32:33] op_sel_hi:[1,0]
	v_pk_add_f32 v[12:13], v[12:13], v[32:33] op_sel_hi:[1,0]
	v_pk_add_f32 v[14:15], v[14:15], v[32:33] op_sel_hi:[1,0]
	v_pk_mul_f32 v[0:1], v[0:1], v[200:201]
	v_pk_mul_f32 v[2:3], v[2:3], v[202:203]
	v_pk_mul_f32 v[4:5], v[4:5], v[204:205]
	v_pk_mul_f32 v[6:7], v[6:7], v[206:207]
	v_pk_mul_f32 v[8:9], v[8:9], v[208:209]
	v_pk_mul_f32 v[10:11], v[10:11], v[210:211]
	v_pk_mul_f32 v[12:13], v[12:13], v[212:213]
	v_pk_mul_f32 v[14:15], v[14:15], v[214:215]
	v_cvt_pk_bf16_f32 v224, v0, v1
	v_cvt_pk_bf16_f32 v225, v2, v3
	v_cvt_pk_bf16_f32 v228, v4, v5
	v_cvt_pk_bf16_f32 v229, v6, v7
	v_cvt_pk_bf16_f32 v226, v8, v9
	v_cvt_pk_bf16_f32 v227, v10, v11
	v_cvt_pk_bf16_f32 v230, v12, v13
	v_cvt_pk_bf16_f32 v231, v14, v15
	s_nop 1
	v_permlane32_swap_b32_e32 v224, v226
	v_permlane32_swap_b32_e32 v225, v227
	v_permlane32_swap_b32_e32 v228, v230
	v_permlane32_swap_b32_e32 v229, v231
	global_store_dwordx4 v234, v[224:227], s[48:49]
	global_store_dwordx4 v234, v[228:231], s[48:49] offset:16
	s_add_u32 s48, s48, 0x40000
	s_addc_u32 s49, s49, 0
	s_add_u32 s45, s45, 1
; __global__ void __launch_bounds__(512, 2) mega_fwd(Args a) {
;     ...
;             {
;                 float xv[16];
;                 xv[0] = bf_lo(r0.x); xv[1] = bf_hi(r0.x); xv[2] = bf_lo(r0.y); xv[3] = bf_hi(r0.y); xv[4] = bf_lo(r0.z); xv[5] = bf_hi(r0.z); xv[6] = bf_lo(r0.w); xv[7] = bf_hi(r0.w);
;                 xv[8] = bf_lo(r1.x); xv[9] = bf_hi(r1.x); xv[10] = bf_lo(r1.y); xv[11] = bf_hi(r1.y); xv[12] = bf_lo(r1.z); xv[13] = bf_hi(r1.z); xv[14] = bf_lo(r1.w); xv[15] = bf_hi(r1.w);
;                 float sm = 0.f;
; #pragma unroll
;                 for (int e = 0; e < 16; ++e) sm += xv[e];
;                 sm += __shfl_xor(sm, 1); sm += __shfl_xor(sm, 2);
;                 const float mu = sm * (1.0f / 64.0f); float q = 0.f;
; #pragma unroll
;                 for (int e = 0; e < 16; ++e) { xv[e] -= mu; q += xv[e] * xv[e]; }
;                 q += __shfl_xor(q, 1); q += __shfl_xor(q, 2);
;                 const float rstd = rsqrtf(q * (1.0f / 64.0f) + EPS);
; #pragma unroll
;                 for (int e = 0; e < 16; ++e) { const float y = xv[e] * rstd * lgv[e >> 2][e & 3] + lbv[e >> 2][e & 3]; VLT[(16 * qd + e) * VLP + jt] = (bf16_t)(pk2(y, 0.f) & 0xffffu); }
;             }
;             const int un = u + ustep;
;             if (ui + 1 < ucnt) { const bf16_t* vp = Z + ((size_t)(un >> 3) * 128 + jt) * NZ + 1024 + (un & 7) * 64 + 16 * qd; r0 = *(const u32x4*)vp; r1 = *(const u32x4*)(vp + 8);
; #pragma unroll
;                 for (int e4 = 0; e4 < 4; ++e4) { lgv[e4] = *(const f32x4*)(KA->gm_ln_g + (un & 7) * 64 + 16 * qd + 4 * e4); lbv[e4] = *(const f32x4*)(KA->gm_ln_b + (un & 7) * 64 + 16 * qd + 4 * e4); } }
;             const int itok = 32 * iblk + r32;
;             const bf16_t* up = Z + (t0 + itok) * NZ + 512 + h * 64 + 32 * dblk + 4 * hi;
;             u32x2 uu[4];
; #pragma unroll
;             for (int g = 0; g < 4; ++g) uu[g] = *(const u32x2*)(up + 8 * g);
;             const float bsp = KA->b_spatial[h * 128 + itok];
;             bf16x8 wf[8];
;             { const bf16_t* wp = WSP + ((size_t)h * 128 + itok) * 128 + 8 * hi;
; #pragma unroll
;               for (int s = 0; s < 8; ++s) if (s < 4 || iblk >= 2) wf[s] = *(const bf16x8*)(wp + 16 * s); }
;             __syncthreads();
;             {
;                 f32x16 acc;
; #pragma unroll
;                 for (int r = 0; r < 16; ++r) acc[r] = 0.f;
.Lp3r_body1:
	s_add_u32 s44, s45, 2
	s_cmp_lt_u32 s44, s18
	s_cbranch_scc0 .Lp3r_tail1
	global_load_dwordx4 v[16:19], v112, s[26:27]
	global_load_dwordx4 v[20:23], v112, s[26:27] offset:16
	global_load_dwordx4 v[24:27], v233, s[26:27]
	global_load_dwordx4 v[28:31], v233, s[26:27] offset:16
	s_add_u32 s26, s26, 0x60000
	s_addc_u32 s27, s27, 0
	s_waitcnt vmcnt(11)
	v_lshlrev_b32_e32 v200, 16, v40
	v_and_b32_e32 v201, s38, v40
	v_lshlrev_b32_e32 v202, 16, v41
	v_and_b32_e32 v203, s38, v41
	v_lshlrev_b32_e32 v204, 16, v42
	v_and_b32_e32 v205, s38, v42
	v_lshlrev_b32_e32 v206, 16, v43
	v_and_b32_e32 v207, s38, v43
	s_waitcnt vmcnt(10)
	v_lshlrev_b32_e32 v208, 16, v44
	v_and_b32_e32 v209, s38, v44
	v_lshlrev_b32_e32 v210, 16, v45
	v_and_b32_e32 v211, s38, v45
	v_lshlrev_b32_e32 v212, 16, v46
	v_and_b32_e32 v213, s38, v46
	v_lshlrev_b32_e32 v214, 16, v47
	v_and_b32_e32 v215, s38, v47
	v_pk_add_f32 v[216:217], v[200:201], v[202:203]
	v_pk_add_f32 v[218:219], v[204:205], v[206:207]
	v_pk_add_f32 v[220:221], v[208:209], v[210:211]
	v_pk_add_f32 v[222:223], v[212:213], v[214:215]
	v_pk_add_f32 v[216:217], v[216:217], v[218:219]
	v_pk_add_f32 v[220:221], v[220:221], v[222:223]
	v_pk_add_f32 v[216:217], v[216:217], v[220:221]
	v_add_f32_e32 v216, v216, v217
	s_nop 1
	v_add_f32_dpp v217, v216, v216 quad_perm:[1,0,3,2] row_mask:0xf bank_mask:0xf
	s_nop 1
	v_add_f32_dpp v216, v217, v217 quad_perm:[2,3,0,1] row_mask:0xf bank_mask:0xf
	v_mul_f32_e32 v216, 0xbc800000, v216
	v_pk_add_f32 v[200:201], v[200:201], v[216:217] op_sel_hi:[1,0]
	v_pk_add_f32 v[202:203], v[202:203], v[216:217] op_sel_hi:[1,0]
	v_pk_add_f32 v[204:205], v[204:205], v[216:217] op_sel_hi:[1,0]
	v_pk_add_f32 v[206:207], v[206:207], v[216:217] op_sel_hi:[1,0]
	v_pk_add_f32 v[208:209], v[208:209], v[216:217] op_sel_hi:[1,0]
	v_pk_add_f32 v[210:211], v[210:211], v[216:217] op_sel_hi:[1,0]
	v_pk_add_f32 v[212:213], v[212:213], v[216:217] op_sel_hi:[1,0]
	v_pk_add_f32 v[214:215], v[214:215], v[216:217] op_sel_hi:[1,0]
	v_pk_mul_f32 v[218:219], v[200:201], v[200:201]
	v_pk_mul_f32 v[220:221], v[202:203], v[202:203]
	v_pk_fma_f32 v[218:219], v[204:205], v[204:205], v[218:219]
	v_pk_fma_f32 v[220:221], v[206:207], v[206:207], v[220:221]
	v_pk_fma_f32 v[218:219], v[208:209], v[208:209], v[218:219]
	v_pk_fma_f32 v[220:221], v[210:211], v[210:211], v[220:221]
	v_pk_fma_f32 v[218:219], v[212:213], v[212:213], v[218:219]
	v_pk_fma_f32 v[220:221], v[214:215], v[214:215], v[220:221]
	v_pk_add_f32 v[218:219], v[218:219], v[220:221]
	v_add_f32_e32 v218, v218, v219
	s_nop 1
	v_add_f32_dpp v219, v218, v218 quad_perm:[1,0,3,2] row_mask:0xf bank_mask:0xf
	s_nop 1
	v_add_f32_dpp v218, v219, v219 quad_perm:[2,3,0,1] row_mask:0xf bank_mask:0xf
	v_fmamk_f32 v218, v218, 0x3c800000, v111
	v_rsq_f32_e32 v218, v218
	s_nop 0
	v_pk_mul_f32 v[200:201], v[200:201], v[218:219] op_sel_hi:[1,0]
	v_pk_mul_f32 v[202:203], v[202:203], v[218:219] op_sel_hi:[1,0]
	v_pk_mul_f32 v[204:205], v[204:205], v[218:219] op_sel_hi:[1,0]
	v_pk_mul_f32 v[206:207], v[206:207], v[218:219] op_sel_hi:[1,0]
	v_pk_mul_f32 v[208:209], v[208:209], v[218:219] op_sel_hi:[1,0]
	v_pk_mul_f32 v[210:211], v[210:211], v[218:219] op_sel_hi:[1,0]
	v_pk_mul_f32 v[212:213], v[212:213], v[218:219] op_sel_hi:[1,0]
	v_pk_mul_f32 v[214:215], v[214:215], v[218:219] op_sel_hi:[1,0]
	v_pk_fma_f32 v[200:201], v[200:201], v[152:153], v[168:169]
	v_pk_fma_f32 v[202:203], v[202:203], v[154:155], v[170:171]
	v_pk_fma_f32 v[204:205], v[204:205], v[156:157], v[172:173]
	v_pk_fma_f32 v[206:207], v[206:207], v[158:159], v[174:175]
	v_pk_fma_f32 v[208:209], v[208:209], v[160:161], v[176:177]
	v_pk_fma_f32 v[210:211], v[210:211], v[162:163], v[178:179]
	v_pk_fma_f32 v[212:213], v[212:213], v[164:165], v[180:181]
	v_pk_fma_f32 v[214:215], v[214:215], v[166:167], v[182:183]
	v_cvt_pk_bf16_f32 v224, v200, v201
	v_cvt_pk_bf16_f32 v225, v202, v203
	v_cvt_pk_bf16_f32 v226, v204, v205
	v_cvt_pk_bf16_f32 v227, v206, v207
	v_cvt_pk_bf16_f32 v228, v208, v209
	v_cvt_pk_bf16_f32 v229, v210, v211
	v_cvt_pk_bf16_f32 v230, v212, v213
	v_cvt_pk_bf16_f32 v231, v214, v215
	ds_write_b16 v117, v224 offset:17408
	ds_write_b16_d16_hi v117, v224 offset:17680
	ds_write_b16 v117, v225 offset:17952
	ds_write_b16_d16_hi v117, v225 offset:18224
	ds_write_b16 v117, v226 offset:18496
	ds_write_b16_d16_hi v117, v226 offset:18768
	ds_write_b16 v117, v227 offset:19040
	ds_write_b16_d16_hi v117, v227 offset:19312
	ds_write_b16 v117, v228 offset:19584
	ds_write_b16_d16_hi v117, v228 offset:19856
	ds_write_b16 v117, v229 offset:20128
	ds_write_b16_d16_hi v117, v229 offset:20400
	ds_write_b16 v117, v230 offset:20672
	ds_write_b16_d16_hi v117, v230 offset:20944
	ds_write_b16 v117, v231 offset:21216
	ds_write_b16_d16_hi v117, v231 offset:21488
	s_waitcnt lgkmcnt(0)
	s_barrier
	ds_read_b128 v[88:91], v118 offset:17408
	ds_read_b128 v[92:95], v118 offset:17440
	ds_read_b128 v[96:99], v118 offset:17472
	ds_read_b128 v[100:103], v118 offset:17504
	s_waitcnt lgkmcnt(3)
	v_mfma_f32_32x32x16_bf16 v[0:15], v[88:91], v[120:123], 0
	s_waitcnt lgkmcnt(2)
	v_mfma_f32_32x32x16_bf16 v[0:15], v[92:95], v[124:127], v[0:15]
	s_waitcnt lgkmcnt(1)
	v_mfma_f32_32x32x16_bf16 v[0:15], v[96:99], v[128:131], v[0:15]
	s_waitcnt lgkmcnt(0)
	v_mfma_f32_32x32x16_bf16 v[0:15], v[100:103], v[132:135], v[0:15]
	s_cmp_lt_u32 s20, 0x100
	s_cbranch_scc1 .Lp3r_half1
	ds_read_b128 v[88:91], v118 offset:17536
	ds_read_b128 v[92:95], v118 offset:17568
	ds_read_b128 v[96:99], v118 offset:17600
	ds_read_b128 v[100:103], v118 offset:17632
	s_waitcnt lgkmcnt(3)
	v_mfma_f32_32x32x16_bf16 v[0:15], v[88:91], v[136:139], v[0:15]
	s_waitcnt lgkmcnt(2)
	v_mfma_f32_32x32x16_bf16 v[0:15], v[92:95], v[140:143], v[0:15]
	s_waitcnt lgkmcnt(1)
	v_mfma_f32_32x32x16_bf16 v[0:15], v[96:99], v[144:147], v[0:15]
	s_waitcnt lgkmcnt(0)
	v_mfma_f32_32x32x16_bf16 v[0:15], v[100:103], v[148:151], v[0:15]
; __global__ void __launch_bounds__(512, 2) mega_fwd(Args a) {
;     ...
;             {
;                 float xv[16];
;                 xv[0] = bf_lo(r0.x); xv[1] = bf_hi(r0.x); xv[2] = bf_lo(r0.y); xv[3] = bf_hi(r0.y); xv[4] = bf_lo(r0.z); xv[5] = bf_hi(r0.z); xv[6] = bf_lo(r0.w); xv[7] = bf_hi(r0.w);
;                 xv[8] = bf_lo(r1.x); xv[9] = bf_hi(r1.x); xv[10] = bf_lo(r1.y); xv[11] = bf_hi(r1.y); xv[12] = bf_lo(r1.z); xv[13] = bf_hi(r1.z); xv[14] = bf_lo(r1.w); xv[15] = bf_hi(r1.w);
;                 float sm = 0.f;
; #pragma unroll
;                 for (int e = 0; e < 16; ++e) sm += xv[e];
;                 sm += __shfl_xor(sm, 1); sm += __shfl_xor(sm, 2);
;                 const float mu = sm * (1.0f / 64.0f); float q = 0.f;
; #pragma unroll
;                 for (int e = 0; e < 16; ++e) { xv[e] -= mu; q += xv[e] * xv[e]; }
;                 q += __shfl_xor(q, 1); q += __shfl_xor(q, 2);
;                 const float rstd = rsqrtf(q * (1.0f / 64.0f) + EPS);
; #pragma unroll
;                 for (int e = 0; e < 16; ++e) { const float y = xv[e] * rstd * lgv[e >> 2][e & 3] + lbv[e >> 2][e & 3]; VLT[(16 * qd + e) * VLP + jt] = (bf16_t)(pk2(y, 0.f) & 0xffffu); }
;             }
;             const int un = u + ustep;
;             if (ui + 1 < ucnt) { const bf16_t* vp = Z + ((size_t)(un >> 3) * 128 + jt) * NZ + 1024 + (un & 7) * 64 + 16 * qd; r0 = *(const u32x4*)vp; r1 = *(const u32x4*)(vp + 8);
; #pragma unroll
;                 for (int e4 = 0; e4 < 4; ++e4) { lgv[e4] = *(const f32x4*)(KA->gm_ln_g + (un & 7) * 64 + 16 * qd + 4 * e4); lbv[e4] = *(const f32x4*)(KA->gm_ln_b + (un & 7) * 64 + 16 * qd + 4 * e4); } }
;             const int itok = 32 * iblk + r32;
;             const bf16_t* up = Z + (t0 + itok) * NZ + 512 + h * 64 + 32 * dblk + 4 * hi;
;             u32x2 uu[4];
; #pragma unroll
;             for (int g = 0; g < 4; ++g) uu[g] = *(const u32x2*)(up + 8 * g);
;             const float bsp = KA->b_spatial[h * 128 + itok];
;             bf16x8 wf[8];
;             { const bf16_t* wp = WSP + ((size_t)h * 128 + itok) * 128 + 8 * hi;
; #pragma unroll
;               for (int s = 0; s < 8; ++s) if (s < 4 || iblk >= 2) wf[s] = *(const bf16x8*)(wp + 16 * s); }
;             __syncthreads();
;             {
;                 f32x16 acc;
; #pragma unroll
;                 for (int r = 0; r < 16; ++r) acc[r] = 0.f;
.Lp3r_half1:
	s_waitcnt vmcnt(8)
	v_permlane32_swap_b32_e32 v48, v50
	v_permlane32_swap_b32_e32 v49, v51
	v_permlane32_swap_b32_e32 v52, v54
	v_permlane32_swap_b32_e32 v53, v55
	s_nop 0
	v_lshlrev_b32_e32 v200, 16, v48
	v_and_b32_e32 v201, s38, v48
	v_lshlrev_b32_e32 v202, 16, v49
	v_and_b32_e32 v203, s38, v49
	v_lshlrev_b32_e32 v204, 16, v52
	v_and_b32_e32 v205, s38, v52
	v_lshlrev_b32_e32 v206, 16, v53
	v_and_b32_e32 v207, s38, v53
	v_lshlrev_b32_e32 v208, 16, v50
	v_and_b32_e32 v209, s38, v50
	v_lshlrev_b32_e32 v210, 16, v51
	v_and_b32_e32 v211, s38, v51
	v_lshlrev_b32_e32 v212, 16, v54
	v_and_b32_e32 v213, s38, v54
	v_lshlrev_b32_e32 v214, 16, v55
	v_and_b32_e32 v215, s38, v55
	s_nop 7
	v_pk_add_f32 v[0:1], v[0:1], v[32:33] op_sel_hi:[1,0]
	v_pk_add_f32 v[2:3], v[2:3], v[32:33] op_sel_hi:[1,0]
	v_pk_add_f32 v[4:5], v[4:5], v[32:33] op_sel_hi:[1,0]
	v_pk_add_f32 v[6:7], v[6:7], v[32:33] op_sel_hi:[1,0]
	v_pk_add_f32 v[8:9], v[8:9], v[32:33] op_sel_hi:[1,0]
	v_pk_add_f32 v[10:11], v[10:11], v[32:33] op_sel_hi:[1,0]
	v_pk_add_f32 v[12:13], v[12:13], v[32:33] op_sel_hi:[1,0]
	v_pk_add_f32 v[14:15], v[14:15], v[32:33] op_sel_hi:[1,0]
	v_pk_mul_f32 v[0:1], v[0:1], v[200:201]
	v_pk_mul_f32 v[2:3], v[2:3], v[202:203]
	v_pk_mul_f32 v[4:5], v[4:5], v[204:205]
	v_pk_mul_f32 v[6:7], v[6:7], v[206:207]
	v_pk_mul_f32 v[8:9], v[8:9], v[208:209]
	v_pk_mul_f32 v[10:11], v[10:11], v[210:211]
	v_pk_mul_f32 v[12:13], v[12:13], v[212:213]
	v_pk_mul_f32 v[14:15], v[14:15], v[214:215]
	v_cvt_pk_bf16_f32 v224, v0, v1
	v_cvt_pk_bf16_f32 v225, v2, v3
	v_cvt_pk_bf16_f32 v228, v4, v5
	v_cvt_pk_bf16_f32 v229, v6, v7
	v_cvt_pk_bf16_f32 v226, v8, v9
	v_cvt_pk_bf16_f32 v227, v10, v11
	v_cvt_pk_bf16_f32 v230, v12, v13
	v_cvt_pk_bf16_f32 v231, v14, v15
	s_nop 1
	v_permlane32_swap_b32_e32 v224, v226
	v_permlane32_swap_b32_e32 v225, v227
	v_permlane32_swap_b32_e32 v228, v230
	v_permlane32_swap_b32_e32 v229, v231
	global_store_dwordx4 v234, v[224:227], s[48:49]
	global_store_dwordx4 v234, v[228:231], s[48:49] offset:16
	s_add_u32 s48, s48, 0x40000
	s_addc_u32 s49, s49, 0
	s_add_u32 s45, s45, 1
.Lp3r_body2:
	s_add_u32 s44, s45, 2
	s_cmp_lt_u32 s44, s18
	s_cbranch_scc0 .Lp3r_tail2
	global_load_dwordx4 v[40:43], v112, s[26:27]
	global_load_dwordx4 v[44:47], v112, s[26:27] offset:16
	global_load_dwordx4 v[48:51], v233, s[26:27]
	global_load_dwordx4 v[52:55], v233, s[26:27] offset:16
	s_add_u32 s26, s26, 0x60000
	s_addc_u32 s27, s27, 0
	s_waitcnt vmcnt(11)
	v_lshlrev_b32_e32 v200, 16, v56
	v_and_b32_e32 v201, s38, v56
	v_lshlrev_b32_e32 v202, 16, v57
	v_and_b32_e32 v203, s38, v57
	v_lshlrev_b32_e32 v204, 16, v58
	v_and_b32_e32 v205, s38, v58
	v_lshlrev_b32_e32 v206, 16, v59
	v_and_b32_e32 v207, s38, v59
	s_waitcnt vmcnt(10)
	v_lshlrev_b32_e32 v208, 16, v60
	v_and_b32_e32 v209, s38, v60
	v_lshlrev_b32_e32 v210, 16, v61
	v_and_b32_e32 v211, s38, v61
	v_lshlrev_b32_e32 v212, 16, v62
	v_and_b32_e32 v213, s38, v62
	v_lshlrev_b32_e32 v214, 16, v63
	v_and_b32_e32 v215, s38, v63
	v_pk_add_f32 v[216:217], v[200:201], v[202:203]
	v_pk_add_f32 v[218:219], v[204:205], v[206:207]
	v_pk_add_f32 v[220:221], v[208:209], v[210:211]
	v_pk_add_f32 v[222:223], v[212:213], v[214:215]
	v_pk_add_f32 v[216:217], v[216:217], v[218:219]
	v_pk_add_f32 v[220:221], v[220:221], v[222:223]
	v_pk_add_f32 v[216:217], v[216:217], v[220:221]
	v_add_f32_e32 v216, v216, v217
	s_nop 1
	v_add_f32_dpp v217, v216, v216 quad_perm:[1,0,3,2] row_mask:0xf bank_mask:0xf
	s_nop 1
	v_add_f32_dpp v216, v217, v217 quad_perm:[2,3,0,1] row_mask:0xf bank_mask:0xf
	v_mul_f32_e32 v216, 0xbc800000, v216
	v_pk_add_f32 v[200:201], v[200:201], v[216:217] op_sel_hi:[1,0]
	v_pk_add_f32 v[202:203], v[202:203], v[216:217] op_sel_hi:[1,0]
	v_pk_add_f32 v[204:205], v[204:205], v[216:217] op_sel_hi:[1,0]
	v_pk_add_f32 v[206:207], v[206:207], v[216:217] op_sel_hi:[1,0]
	v_pk_add_f32 v[208:209], v[208:209], v[216:217] op_sel_hi:[1,0]
	v_pk_add_f32 v[210:211], v[210:211], v[216:217] op_sel_hi:[1,0]
	v_pk_add_f32 v[212:213], v[212:213], v[216:217] op_sel_hi:[1,0]
	v_pk_add_f32 v[214:215], v[214:215], v[216:217] op_sel_hi:[1,0]
	v_pk_mul_f32 v[218:219], v[200:201], v[200:201]
	v_pk_mul_f32 v[220:221], v[202:203], v[202:203]
	v_pk_fma_f32 v[218:219], v[204:205], v[204:205], v[218:219]
	v_pk_fma_f32 v[220:221], v[206:207], v[206:207], v[220:221]
	v_pk_fma_f32 v[218:219], v[208:209], v[208:209], v[218:219]
	v_pk_fma_f32 v[220:221], v[210:211], v[210:211], v[220:221]
	v_pk_fma_f32 v[218:219], v[212:213], v[212:213], v[218:219]
	v_pk_fma_f32 v[220:221], v[214:215], v[214:215], v[220:221]
	v_pk_add_f32 v[218:219], v[218:219], v[220:221]
	v_add_f32_e32 v218, v218, v219
	s_nop 1
	v_add_f32_dpp v219, v218, v218 quad_perm:[1,0,3,2] row_mask:0xf bank_mask:0xf
	s_nop 1
	v_add_f32_dpp v218, v219, v219 quad_perm:[2,3,0,1] row_mask:0xf bank_mask:0xf
	v_fmamk_f32 v218, v218, 0x3c800000, v111
	v_rsq_f32_e32 v218, v218
	s_nop 0
	v_pk_mul_f32 v[200:201], v[200:201], v[218:219] op_sel_hi:[1,0]
	v_pk_mul_f32 v[202:203], v[202:203], v[218:219] op_sel_hi:[1,0]
	v_pk_mul_f32 v[204:205], v[204:205], v[218:219] op_sel_hi:[1,0]
	v_pk_mul_f32 v[206:207], v[206:207], v[218:219] op_sel_hi:[1,0]
	v_pk_mul_f32 v[208:209], v[208:209], v[218:219] op_sel_hi:[1,0]
	v_pk_mul_f32 v[210:211], v[210:211], v[218:219] op_sel_hi:[1,0]
	v_pk_mul_f32 v[212:213], v[212:213], v[218:219] op_sel_hi:[1,0]
	v_pk_mul_f32 v[214:215], v[214:215], v[218:219] op_sel_hi:[1,0]
	v_pk_fma_f32 v[200:201], v[200:201], v[152:153], v[168:169]
	v_pk_fma_f32 v[202:203], v[202:203], v[154:155], v[170:171]
	v_pk_fma_f32 v[204:205], v[204:205], v[156:157], v[172:173]
	v_pk_fma_f32 v[206:207], v[206:207], v[158:159], v[174:175]
	v_pk_fma_f32 v[208:209], v[208:209], v[160:161], v[176:177]
	v_pk_fma_f32 v[210:211], v[210:211], v[162:163], v[178:179]
	v_pk_fma_f32 v[212:213], v[212:213], v[164:165], v[180:181]
	v_pk_fma_f32 v[214:215], v[214:215], v[166:167], v[182:183]
	v_cvt_pk_bf16_f32 v224, v200, v201
	v_cvt_pk_bf16_f32 v225, v202, v203
	v_cvt_pk_bf16_f32 v226, v204, v205
	v_cvt_pk_bf16_f32 v227, v206, v207
	v_cvt_pk_bf16_f32 v228, v208, v209
	v_cvt_pk_bf16_f32 v229, v210, v211
	v_cvt_pk_bf16_f32 v230, v212, v213
	v_cvt_pk_bf16_f32 v231, v214, v215
	ds_write_b16 v117, v224 offset:34816
	ds_write_b16_d16_hi v117, v224 offset:35088
	ds_write_b16 v117, v225 offset:35360
	ds_write_b16_d16_hi v117, v225 offset:35632
	ds_write_b16 v117, v226 offset:35904
	ds_write_b16_d16_hi v117, v226 offset:36176
	ds_write_b16 v117, v227 offset:36448
	ds_write_b16_d16_hi v117, v227 offset:36720
	ds_write_b16 v117, v228 offset:36992
	ds_write_b16_d16_hi v117, v228 offset:37264
	ds_write_b16 v117, v229 offset:37536
	ds_write_b16_d16_hi v117, v229 offset:37808
	ds_write_b16 v117, v230 offset:38080
	ds_write_b16_d16_hi v117, v230 offset:38352
	ds_write_b16 v117, v231 offset:38624
	ds_write_b16_d16_hi v117, v231 offset:38896
	s_waitcnt lgkmcnt(0)
	s_barrier
; #define LAS __attribute__((address_space(3)))
; __device__ __forceinline__ unsigned pk2(float lo, float hi) { f32x2_t v = {lo, hi}; bf16x2_t b = __builtin_convertvector(v, bf16x2_t); return __builtin_bit_cast(unsigned, b); }
; __device__ __forceinline__ float bf_lo(unsigned u) { return __uint_as_float(u << 16); }
; __device__ __forceinline__ float bf_hi(unsigned u) { return __uint_as_float(u & 0xffff0000u); }
; __global__ void __launch_bounds__(512, 2) mega_fwd(Args a) {
;     ...
;             {
;                 float xv[16];
;                 xv[0] = bf_lo(r0.x); xv[1] = bf_hi(r0.x); xv[2] = bf_lo(r0.y); xv[3] = bf_hi(r0.y); xv[4] = bf_lo(r0.z); xv[5] = bf_hi(r0.z); xv[6] = bf_lo(r0.w); xv[7] = bf_hi(r0.w);
;                 xv[8] = bf_lo(r1.x); xv[9] = bf_hi(r1.x); xv[10] = bf_lo(r1.y); xv[11] = bf_hi(r1.y); xv[12] = bf_lo(r1.z); xv[13] = bf_hi(r1.z); xv[14] = bf_lo(r1.w); xv[15] = bf_hi(r1.w);
;                 float sm = 0.f;
; #pragma unroll
;                 for (int e = 0; e < 16; ++e) sm += xv[e];
;                 sm += __shfl_xor(sm, 1); sm += __shfl_xor(sm, 2);
;                 const float mu = sm * (1.0f / 64.0f); float q = 0.f;
; #pragma unroll
;                 for (int e = 0; e < 16; ++e) { xv[e] -= mu; q += xv[e] * xv[e]; }
;                 q += __shfl_xor(q, 1); q += __shfl_xor(q, 2);
;                 const float rstd = rsqrtf(q * (1.0f / 64.0f) + EPS);
;     ...
;             {
;                 f32x16 acc;
; #pragma unroll
;                 for (int r = 0; r < 16; ++r) acc[r] = 0.f;
;                 const LAS bf16_t* vl = VLT + (32 * dblk + r32) * VLP + 8 * hi;
; #pragma unroll
;                 for (int s = 0; s < 8; ++s) if (s < 4 || iblk >= 2) {
;                     const bf16x8 vf = *(const LAS bf16x8*)(vl + 16 * s);
;                     acc = __builtin_amdgcn_mfma_f32_32x32x16_bf16(vf, wf[s], acc, 0, 0, 0);
;                 }
;                 bf16_t* op = AO + (t0 + itok) * DM + 512 + h * 64 + 32 * dblk + 4 * hi;
; #pragma unroll
;                 for (int g = 0; g < 4; ++g) {
;                     u32x2 w; w.x = pk2(bf_lo(uu[g].x) * (acc[4 * g] + bsp), bf_hi(uu[g].x) * (acc[4 * g + 1] + bsp)); w.y = pk2(bf_lo(uu[g].y) * (acc[4 * g + 2] + bsp), bf_hi(uu[g].y) * (acc[4 * g + 3] + bsp));
;                     *(u32x2*)(op + 8 * g) = w;
;                 }
	ds_read_b128 v[88:91], v118 offset:34816
	ds_read_b128 v[92:95], v118 offset:34848
	ds_read_b128 v[96:99], v118 offset:34880
	ds_read_b128 v[100:103], v118 offset:34912
	s_waitcnt lgkmcnt(3)
	v_mfma_f32_32x32x16_bf16 v[0:15], v[88:91], v[120:123], 0
	s_waitcnt lgkmcnt(2)
	v_mfma_f32_32x32x16_bf16 v[0:15], v[92:95], v[124:127], v[0:15]
	s_waitcnt lgkmcnt(1)
	v_mfma_f32_32x32x16_bf16 v[0:15], v[96:99], v[128:131], v[0:15]
	s_waitcnt lgkmcnt(0)
	v_mfma_f32_32x32x16_bf16 v[0:15], v[100:103], v[132:135], v[0:15]
	s_cmp_lt_u32 s20, 0x100
	s_cbranch_scc1 .Lp3r_half2
	ds_read_b128 v[88:91], v118 offset:34944
	ds_read_b128 v[92:95], v118 offset:34976
	ds_read_b128 v[96:99], v118 offset:35008
	ds_read_b128 v[100:103], v118 offset:35040
	s_waitcnt lgkmcnt(3)
	v_mfma_f32_32x32x16_bf16 v[0:15], v[88:91], v[136:139], v[0:15]
	s_waitcnt lgkmcnt(2)
	v_mfma_f32_32x32x16_bf16 v[0:15], v[92:95], v[140:143], v[0:15]
	s_waitcnt lgkmcnt(1)
	v_mfma_f32_32x32x16_bf16 v[0:15], v[96:99], v[144:147], v[0:15]
	s_waitcnt lgkmcnt(0)
	v_mfma_f32_32x32x16_bf16 v[0:15], v[100:103], v[148:151], v[0:15]
.Lp3r_half2:
	s_waitcnt vmcnt(8)
	v_permlane32_swap_b32_e32 v64, v66
	v_permlane32_swap_b32_e32 v65, v67
	v_permlane32_swap_b32_e32 v68, v70
	v_permlane32_swap_b32_e32 v69, v71
	s_nop 0
	v_lshlrev_b32_e32 v200, 16, v64
	v_and_b32_e32 v201, s38, v64
	v_lshlrev_b32_e32 v202, 16, v65
	v_and_b32_e32 v203, s38, v65
	v_lshlrev_b32_e32 v204, 16, v68
	v_and_b32_e32 v205, s38, v68
	v_lshlrev_b32_e32 v206, 16, v69
	v_and_b32_e32 v207, s38, v69
	v_lshlrev_b32_e32 v208, 16, v66
	v_and_b32_e32 v209, s38, v66
	v_lshlrev_b32_e32 v210, 16, v67
	v_and_b32_e32 v211, s38, v67
	v_lshlrev_b32_e32 v212, 16, v70
	v_and_b32_e32 v213, s38, v70
	v_lshlrev_b32_e32 v214, 16, v71
	v_and_b32_e32 v215, s38, v71
	s_nop 7
	v_pk_add_f32 v[0:1], v[0:1], v[32:33] op_sel_hi:[1,0]
	v_pk_add_f32 v[2:3], v[2:3], v[32:33] op_sel_hi:[1,0]
	v_pk_add_f32 v[4:5], v[4:5], v[32:33] op_sel_hi:[1,0]
	v_pk_add_f32 v[6:7], v[6:7], v[32:33] op_sel_hi:[1,0]
	v_pk_add_f32 v[8:9], v[8:9], v[32:33] op_sel_hi:[1,0]
	v_pk_add_f32 v[10:11], v[10:11], v[32:33] op_sel_hi:[1,0]
	v_pk_add_f32 v[12:13], v[12:13], v[32:33] op_sel_hi:[1,0]
	v_pk_add_f32 v[14:15], v[14:15], v[32:33] op_sel_hi:[1,0]
	v_pk_mul_f32 v[0:1], v[0:1], v[200:201]
	v_pk_mul_f32 v[2:3], v[2:3], v[202:203]
	v_pk_mul_f32 v[4:5], v[4:5], v[204:205]
	v_pk_mul_f32 v[6:7], v[6:7], v[206:207]
	v_pk_mul_f32 v[8:9], v[8:9], v[208:209]
	v_pk_mul_f32 v[10:11], v[10:11], v[210:211]
	v_pk_mul_f32 v[12:13], v[12:13], v[212:213]
	v_pk_mul_f32 v[14:15], v[14:15], v[214:215]
	v_cvt_pk_bf16_f32 v224, v0, v1
	v_cvt_pk_bf16_f32 v225, v2, v3
	v_cvt_pk_bf16_f32 v228, v4, v5
	v_cvt_pk_bf16_f32 v229, v6, v7
	v_cvt_pk_bf16_f32 v226, v8, v9
	v_cvt_pk_bf16_f32 v227, v10, v11
	v_cvt_pk_bf16_f32 v230, v12, v13
	v_cvt_pk_bf16_f32 v231, v14, v15
	s_nop 1
	v_permlane32_swap_b32_e32 v224, v226
	v_permlane32_swap_b32_e32 v225, v227
	v_permlane32_swap_b32_e32 v228, v230
	v_permlane32_swap_b32_e32 v229, v231
	global_store_dwordx4 v234, v[224:227], s[48:49]
	global_store_dwordx4 v234, v[228:231], s[48:49] offset:16
	s_add_u32 s48, s48, 0x40000
	s_addc_u32 s49, s49, 0
	s_add_u32 s45, s45, 1
	s_branch .Lp3r_body0
.Lp3r_tail0:
	s_waitcnt vmcnt(3)
	v_lshlrev_b32_e32 v200, 16, v16
	v_and_b32_e32 v201, s38, v16
	v_lshlrev_b32_e32 v202, 16, v17
	v_and_b32_e32 v203, s38, v17
	v_lshlrev_b32_e32 v204, 16, v18
	v_and_b32_e32 v205, s38, v18
	v_lshlrev_b32_e32 v206, 16, v19
	v_and_b32_e32 v207, s38, v19
	s_waitcnt vmcnt(2)
	v_lshlrev_b32_e32 v208, 16, v20
	v_and_b32_e32 v209, s38, v20
	v_lshlrev_b32_e32 v210, 16, v21
	v_and_b32_e32 v211, s38, v21
	v_lshlrev_b32_e32 v212, 16, v22
	v_and_b32_e32 v213, s38, v22
	v_lshlrev_b32_e32 v214, 16, v23
	v_and_b32_e32 v215, s38, v23
	v_pk_add_f32 v[216:217], v[200:201], v[202:203]
	v_pk_add_f32 v[218:219], v[204:205], v[206:207]
	v_pk_add_f32 v[220:221], v[208:209], v[210:211]
	v_pk_add_f32 v[222:223], v[212:213], v[214:215]
	v_pk_add_f32 v[216:217], v[216:217], v[218:219]
	v_pk_add_f32 v[220:221], v[220:221], v[222:223]
	v_pk_add_f32 v[216:217], v[216:217], v[220:221]
	v_add_f32_e32 v216, v216, v217
	s_nop 1
	v_add_f32_dpp v217, v216, v216 quad_perm:[1,0,3,2] row_mask:0xf bank_mask:0xf
	s_nop 1
	v_add_f32_dpp v216, v217, v217 quad_perm:[2,3,0,1] row_mask:0xf bank_mask:0xf
	v_mul_f32_e32 v216, 0xbc800000, v216
	v_pk_add_f32 v[200:201], v[200:201], v[216:217] op_sel_hi:[1,0]
	v_pk_add_f32 v[202:203], v[202:203], v[216:217] op_sel_hi:[1,0]
	v_pk_add_f32 v[204:205], v[204:205], v[216:217] op_sel_hi:[1,0]
	v_pk_add_f32 v[206:207], v[206:207], v[216:217] op_sel_hi:[1,0]
	v_pk_add_f32 v[208:209], v[208:209], v[216:217] op_sel_hi:[1,0]
	v_pk_add_f32 v[210:211], v[210:211], v[216:217] op_sel_hi:[1,0]
	v_pk_add_f32 v[212:213], v[212:213], v[216:217] op_sel_hi:[1,0]
	v_pk_add_f32 v[214:215], v[214:215], v[216:217] op_sel_hi:[1,0]
	v_pk_mul_f32 v[218:219], v[200:201], v[200:201]
	v_pk_mul_f32 v[220:221], v[202:203], v[202:203]
	v_pk_fma_f32 v[218:219], v[204:205], v[204:205], v[218:219]
	v_pk_fma_f32 v[220:221], v[206:207], v[206:207], v[220:221]
	v_pk_fma_f32 v[218:219], v[208:209], v[208:209], v[218:219]
	v_pk_fma_f32 v[220:221], v[210:211], v[210:211], v[220:221]
	v_pk_fma_f32 v[218:219], v[212:213], v[212:213], v[218:219]
	v_pk_fma_f32 v[220:221], v[214:215], v[214:215], v[220:221]
	v_pk_add_f32 v[218:219], v[218:219], v[220:221]
	v_add_f32_e32 v218, v218, v219
	s_nop 1
	v_add_f32_dpp v219, v218, v218 quad_perm:[1,0,3,2] row_mask:0xf bank_mask:0xf
	s_nop 1
	v_add_f32_dpp v218, v219, v219 quad_perm:[2,3,0,1] row_mask:0xf bank_mask:0xf
	v_fmamk_f32 v218, v218, 0x3c800000, v111
; #define LAS __attribute__((address_space(3)))
; __global__ void __launch_bounds__(512, 2) mega_fwd(Args a) {
;     ...
;                 const float rstd = rsqrtf(q * (1.0f / 64.0f) + EPS);
; #pragma unroll
;                 for (int e = 0; e < 16; ++e) { const float y = xv[e] * rstd * lgv[e >> 2][e & 3] + lbv[e >> 2][e & 3]; VLT[(16 * qd + e) * VLP + jt] = (bf16_t)(pk2(y, 0.f) & 0xffffu); }
;             }
;             const int un = u + ustep;
;             if (ui + 1 < ucnt) { const bf16_t* vp = Z + ((size_t)(un >> 3) * 128 + jt) * NZ + 1024 + (un & 7) * 64 + 16 * qd; r0 = *(const u32x4*)vp; r1 = *(const u32x4*)(vp + 8);
; #pragma unroll
;                 for (int e4 = 0; e4 < 4; ++e4) { lgv[e4] = *(const f32x4*)(KA->gm_ln_g + (un & 7) * 64 + 16 * qd + 4 * e4); lbv[e4] = *(const f32x4*)(KA->gm_ln_b + (un & 7) * 64 + 16 * qd + 4 * e4); } }
;             const int itok = 32 * iblk + r32;
;             const bf16_t* up = Z + (t0 + itok) * NZ + 512 + h * 64 + 32 * dblk + 4 * hi;
;             u32x2 uu[4];
; #pragma unroll
;             for (int g = 0; g < 4; ++g) uu[g] = *(const u32x2*)(up + 8 * g);
;             const float bsp = KA->b_spatial[h * 128 + itok];
;             bf16x8 wf[8];
;             { const bf16_t* wp = WSP + ((size_t)h * 128 + itok) * 128 + 8 * hi;
; #pragma unroll
;               for (int s = 0; s < 8; ++s) if (s < 4 || iblk >= 2) wf[s] = *(const bf16x8*)(wp + 16 * s); }
;             __syncthreads();
;             {
;                 f32x16 acc;
; #pragma unroll
;                 for (int r = 0; r < 16; ++r) acc[r] = 0.f;
;                 const LAS bf16_t* vl = VLT + (32 * dblk + r32) * VLP + 8 * hi;
; #pragma unroll
;                 for (int s = 0; s < 8; ++s) if (s < 4 || iblk >= 2) {
;                     const bf16x8 vf = *(const LAS bf16x8*)(vl + 16 * s);
;                     acc = __builtin_amdgcn_mfma_f32_32x32x16_bf16(vf, wf[s], acc, 0, 0, 0);
;                 }
;                 bf16_t* op = AO + (t0 + itok) * DM + 512 + h * 64 + 32 * dblk + 4 * hi;
; #pragma unroll
;                 for (int g = 0; g < 4; ++g) {
;                     u32x2 w; w.x = pk2(bf_lo(uu[g].x) * (acc[4 * g] + bsp), bf_hi(uu[g].x) * (acc[4 * g + 1] + bsp)); w.y = pk2(bf_lo(uu[g].y) * (acc[4 * g + 2] + bsp), bf_hi(uu[g].y) * (acc[4 * g + 3] + bsp));
;                     *(u32x2*)(op + 8 * g) = w;
;                 }
	v_rsq_f32_e32 v218, v218
	s_nop 0
	v_pk_mul_f32 v[200:201], v[200:201], v[218:219] op_sel_hi:[1,0]
	v_pk_mul_f32 v[202:203], v[202:203], v[218:219] op_sel_hi:[1,0]
	v_pk_mul_f32 v[204:205], v[204:205], v[218:219] op_sel_hi:[1,0]
	v_pk_mul_f32 v[206:207], v[206:207], v[218:219] op_sel_hi:[1,0]
	v_pk_mul_f32 v[208:209], v[208:209], v[218:219] op_sel_hi:[1,0]
	v_pk_mul_f32 v[210:211], v[210:211], v[218:219] op_sel_hi:[1,0]
	v_pk_mul_f32 v[212:213], v[212:213], v[218:219] op_sel_hi:[1,0]
	v_pk_mul_f32 v[214:215], v[214:215], v[218:219] op_sel_hi:[1,0]
	v_pk_fma_f32 v[200:201], v[200:201], v[152:153], v[168:169]
	v_pk_fma_f32 v[202:203], v[202:203], v[154:155], v[170:171]
	v_pk_fma_f32 v[204:205], v[204:205], v[156:157], v[172:173]
	v_pk_fma_f32 v[206:207], v[206:207], v[158:159], v[174:175]
	v_pk_fma_f32 v[208:209], v[208:209], v[160:161], v[176:177]
	v_pk_fma_f32 v[210:211], v[210:211], v[162:163], v[178:179]
	v_pk_fma_f32 v[212:213], v[212:213], v[164:165], v[180:181]
	v_pk_fma_f32 v[214:215], v[214:215], v[166:167], v[182:183]
	v_cvt_pk_bf16_f32 v224, v200, v201
	v_cvt_pk_bf16_f32 v225, v202, v203
	v_cvt_pk_bf16_f32 v226, v204, v205
	v_cvt_pk_bf16_f32 v227, v206, v207
	v_cvt_pk_bf16_f32 v228, v208, v209
	v_cvt_pk_bf16_f32 v229, v210, v211
	v_cvt_pk_bf16_f32 v230, v212, v213
	v_cvt_pk_bf16_f32 v231, v214, v215
	ds_write_b16 v117, v224 offset:0
	ds_write_b16_d16_hi v117, v224 offset:272
	ds_write_b16 v117, v225 offset:544
	ds_write_b16_d16_hi v117, v225 offset:816
	ds_write_b16 v117, v226 offset:1088
	ds_write_b16_d16_hi v117, v226 offset:1360
	ds_write_b16 v117, v227 offset:1632
	ds_write_b16_d16_hi v117, v227 offset:1904
	ds_write_b16 v117, v228 offset:2176
	ds_write_b16_d16_hi v117, v228 offset:2448
	ds_write_b16 v117, v229 offset:2720
	ds_write_b16_d16_hi v117, v229 offset:2992
	ds_write_b16 v117, v230 offset:3264
	ds_write_b16_d16_hi v117, v230 offset:3536
	ds_write_b16 v117, v231 offset:3808
	ds_write_b16_d16_hi v117, v231 offset:4080
	s_waitcnt lgkmcnt(0)
	s_barrier
	ds_read_b128 v[88:91], v118 offset:0
	ds_read_b128 v[92:95], v118 offset:32
	ds_read_b128 v[96:99], v118 offset:64
	ds_read_b128 v[100:103], v118 offset:96
	s_waitcnt lgkmcnt(3)
	v_mfma_f32_32x32x16_bf16 v[0:15], v[88:91], v[120:123], 0
	s_waitcnt lgkmcnt(2)
	v_mfma_f32_32x32x16_bf16 v[0:15], v[92:95], v[124:127], v[0:15]
	s_waitcnt lgkmcnt(1)
	v_mfma_f32_32x32x16_bf16 v[0:15], v[96:99], v[128:131], v[0:15]
	s_waitcnt lgkmcnt(0)
	v_mfma_f32_32x32x16_bf16 v[0:15], v[100:103], v[132:135], v[0:15]
	s_cmp_lt_u32 s20, 0x100
	s_cbranch_scc1 .Lp3r_halft0
	ds_read_b128 v[88:91], v118 offset:128
	ds_read_b128 v[92:95], v118 offset:160
	ds_read_b128 v[96:99], v118 offset:192
	ds_read_b128 v[100:103], v118 offset:224
	s_waitcnt lgkmcnt(3)
	v_mfma_f32_32x32x16_bf16 v[0:15], v[88:91], v[136:139], v[0:15]
	s_waitcnt lgkmcnt(2)
	v_mfma_f32_32x32x16_bf16 v[0:15], v[92:95], v[140:143], v[0:15]
	s_waitcnt lgkmcnt(1)
	v_mfma_f32_32x32x16_bf16 v[0:15], v[96:99], v[144:147], v[0:15]
	s_waitcnt lgkmcnt(0)
	v_mfma_f32_32x32x16_bf16 v[0:15], v[100:103], v[148:151], v[0:15]
.Lp3r_halft0:
	s_waitcnt vmcnt(0)
	v_permlane32_swap_b32_e32 v24, v26
	v_permlane32_swap_b32_e32 v25, v27
	v_permlane32_swap_b32_e32 v28, v30
	v_permlane32_swap_b32_e32 v29, v31
	s_nop 0
	v_lshlrev_b32_e32 v200, 16, v24
	v_and_b32_e32 v201, s38, v24
	v_lshlrev_b32_e32 v202, 16, v25
	v_and_b32_e32 v203, s38, v25
	v_lshlrev_b32_e32 v204, 16, v28
	v_and_b32_e32 v205, s38, v28
	v_lshlrev_b32_e32 v206, 16, v29
	v_and_b32_e32 v207, s38, v29
	v_lshlrev_b32_e32 v208, 16, v26
	v_and_b32_e32 v209, s38, v26
	v_lshlrev_b32_e32 v210, 16, v27
	v_and_b32_e32 v211, s38, v27
	v_lshlrev_b32_e32 v212, 16, v30
	v_and_b32_e32 v213, s38, v30
	v_lshlrev_b32_e32 v214, 16, v31
	v_and_b32_e32 v215, s38, v31
	s_nop 7
	v_pk_add_f32 v[0:1], v[0:1], v[32:33] op_sel_hi:[1,0]
	v_pk_add_f32 v[2:3], v[2:3], v[32:33] op_sel_hi:[1,0]
	v_pk_add_f32 v[4:5], v[4:5], v[32:33] op_sel_hi:[1,0]
	v_pk_add_f32 v[6:7], v[6:7], v[32:33] op_sel_hi:[1,0]
	v_pk_add_f32 v[8:9], v[8:9], v[32:33] op_sel_hi:[1,0]
	v_pk_add_f32 v[10:11], v[10:11], v[32:33] op_sel_hi:[1,0]
	v_pk_add_f32 v[12:13], v[12:13], v[32:33] op_sel_hi:[1,0]
	v_pk_add_f32 v[14:15], v[14:15], v[32:33] op_sel_hi:[1,0]
	v_pk_mul_f32 v[0:1], v[0:1], v[200:201]
	v_pk_mul_f32 v[2:3], v[2:3], v[202:203]
	v_pk_mul_f32 v[4:5], v[4:5], v[204:205]
	v_pk_mul_f32 v[6:7], v[6:7], v[206:207]
	v_pk_mul_f32 v[8:9], v[8:9], v[208:209]
	v_pk_mul_f32 v[10:11], v[10:11], v[210:211]
	v_pk_mul_f32 v[12:13], v[12:13], v[212:213]
	v_pk_mul_f32 v[14:15], v[14:15], v[214:215]
	v_cvt_pk_bf16_f32 v224, v0, v1
	v_cvt_pk_bf16_f32 v225, v2, v3
	v_cvt_pk_bf16_f32 v228, v4, v5
	v_cvt_pk_bf16_f32 v229, v6, v7
	v_cvt_pk_bf16_f32 v226, v8, v9
	v_cvt_pk_bf16_f32 v227, v10, v11
	v_cvt_pk_bf16_f32 v230, v12, v13
	v_cvt_pk_bf16_f32 v231, v14, v15
	s_nop 1
	v_permlane32_swap_b32_e32 v224, v226
	v_permlane32_swap_b32_e32 v225, v227
	v_permlane32_swap_b32_e32 v228, v230
	v_permlane32_swap_b32_e32 v229, v231
	global_store_dwordx4 v234, v[224:227], s[48:49]
	global_store_dwordx4 v234, v[228:231], s[48:49] offset:16
	s_add_u32 s48, s48, 0x40000
	s_addc_u32 s49, s49, 0
	s_add_u32 s45, s45, 1
	s_cmp_lt_u32 s45, s18
	s_cbranch_scc0 .Lp3_done
; __global__ void __launch_bounds__(512, 2) mega_fwd(Args a) {
;     ...
;             {
;                 float xv[16];
;                 xv[0] = bf_lo(r0.x); xv[1] = bf_hi(r0.x); xv[2] = bf_lo(r0.y); xv[3] = bf_hi(r0.y); xv[4] = bf_lo(r0.z); xv[5] = bf_hi(r0.z); xv[6] = bf_lo(r0.w); xv[7] = bf_hi(r0.w);
;                 xv[8] = bf_lo(r1.x); xv[9] = bf_hi(r1.x); xv[10] = bf_lo(r1.y); xv[11] = bf_hi(r1.y); xv[12] = bf_lo(r1.z); xv[13] = bf_hi(r1.z); xv[14] = bf_lo(r1.w); xv[15] = bf_hi(r1.w);
;                 float sm = 0.f;
; #pragma unroll
;                 for (int e = 0; e < 16; ++e) sm += xv[e];
;                 sm += __shfl_xor(sm, 1); sm += __shfl_xor(sm, 2);
;                 const float mu = sm * (1.0f / 64.0f); float q = 0.f;
; #pragma unroll
;                 for (int e = 0; e < 16; ++e) { xv[e] -= mu; q += xv[e] * xv[e]; }
;                 q += __shfl_xor(q, 1); q += __shfl_xor(q, 2);
;                 const float rstd = rsqrtf(q * (1.0f / 64.0f) + EPS);
; #pragma unroll
;                 for (int e = 0; e < 16; ++e) { const float y = xv[e] * rstd * lgv[e >> 2][e & 3] + lbv[e >> 2][e & 3]; VLT[(16 * qd + e) * VLP + jt] = (bf16_t)(pk2(y, 0.f) & 0xffffu); }
;             }
;             const int un = u + ustep;
;             if (ui + 1 < ucnt) { const bf16_t* vp = Z + ((size_t)(un >> 3) * 128 + jt) * NZ + 1024 + (un & 7) * 64 + 16 * qd; r0 = *(const u32x4*)vp; r1 = *(const u32x4*)(vp + 8);
; #pragma unroll
;                 for (int e4 = 0; e4 < 4; ++e4) { lgv[e4] = *(const f32x4*)(KA->gm_ln_g + (un & 7) * 64 + 16 * qd + 4 * e4); lbv[e4] = *(const f32x4*)(KA->gm_ln_b + (un & 7) * 64 + 16 * qd + 4 * e4); } }
;             const int itok = 32 * iblk + r32;
;             const bf16_t* up = Z + (t0 + itok) * NZ + 512 + h * 64 + 32 * dblk + 4 * hi;
;             u32x2 uu[4];
; #pragma unroll
;             for (int g = 0; g < 4; ++g) uu[g] = *(const u32x2*)(up + 8 * g);
;             const float bsp = KA->b_spatial[h * 128 + itok];
;             bf16x8 wf[8];
;             { const bf16_t* wp = WSP + ((size_t)h * 128 + itok) * 128 + 8 * hi;
; #pragma unroll
;               for (int s = 0; s < 8; ++s) if (s < 4 || iblk >= 2) wf[s] = *(const bf16x8*)(wp + 16 * s); }
;             __syncthreads();
;             {
;                 f32x16 acc;
; #pragma unroll
;                 for (int r = 0; r < 16; ++r) acc[r] = 0.f;
.Lp3r_tail1:
	s_waitcnt vmcnt(3)
	v_lshlrev_b32_e32 v200, 16, v40
	v_and_b32_e32 v201, s38, v40
	v_lshlrev_b32_e32 v202, 16, v41
	v_and_b32_e32 v203, s38, v41
	v_lshlrev_b32_e32 v204, 16, v42
	v_and_b32_e32 v205, s38, v42
	v_lshlrev_b32_e32 v206, 16, v43
	v_and_b32_e32 v207, s38, v43
	s_waitcnt vmcnt(2)
	v_lshlrev_b32_e32 v208, 16, v44
	v_and_b32_e32 v209, s38, v44
	v_lshlrev_b32_e32 v210, 16, v45
	v_and_b32_e32 v211, s38, v45
	v_lshlrev_b32_e32 v212, 16, v46
	v_and_b32_e32 v213, s38, v46
	v_lshlrev_b32_e32 v214, 16, v47
	v_and_b32_e32 v215, s38, v47
	v_pk_add_f32 v[216:217], v[200:201], v[202:203]
	v_pk_add_f32 v[218:219], v[204:205], v[206:207]
	v_pk_add_f32 v[220:221], v[208:209], v[210:211]
	v_pk_add_f32 v[222:223], v[212:213], v[214:215]
	v_pk_add_f32 v[216:217], v[216:217], v[218:219]
	v_pk_add_f32 v[220:221], v[220:221], v[222:223]
	v_pk_add_f32 v[216:217], v[216:217], v[220:221]
	v_add_f32_e32 v216, v216, v217
	s_nop 1
	v_add_f32_dpp v217, v216, v216 quad_perm:[1,0,3,2] row_mask:0xf bank_mask:0xf
	s_nop 1
	v_add_f32_dpp v216, v217, v217 quad_perm:[2,3,0,1] row_mask:0xf bank_mask:0xf
	v_mul_f32_e32 v216, 0xbc800000, v216
	v_pk_add_f32 v[200:201], v[200:201], v[216:217] op_sel_hi:[1,0]
	v_pk_add_f32 v[202:203], v[202:203], v[216:217] op_sel_hi:[1,0]
	v_pk_add_f32 v[204:205], v[204:205], v[216:217] op_sel_hi:[1,0]
	v_pk_add_f32 v[206:207], v[206:207], v[216:217] op_sel_hi:[1,0]
	v_pk_add_f32 v[208:209], v[208:209], v[216:217] op_sel_hi:[1,0]
	v_pk_add_f32 v[210:211], v[210:211], v[216:217] op_sel_hi:[1,0]
	v_pk_add_f32 v[212:213], v[212:213], v[216:217] op_sel_hi:[1,0]
	v_pk_add_f32 v[214:215], v[214:215], v[216:217] op_sel_hi:[1,0]
	v_pk_mul_f32 v[218:219], v[200:201], v[200:201]
	v_pk_mul_f32 v[220:221], v[202:203], v[202:203]
	v_pk_fma_f32 v[218:219], v[204:205], v[204:205], v[218:219]
	v_pk_fma_f32 v[220:221], v[206:207], v[206:207], v[220:221]
	v_pk_fma_f32 v[218:219], v[208:209], v[208:209], v[218:219]
	v_pk_fma_f32 v[220:221], v[210:211], v[210:211], v[220:221]
	v_pk_fma_f32 v[218:219], v[212:213], v[212:213], v[218:219]
	v_pk_fma_f32 v[220:221], v[214:215], v[214:215], v[220:221]
	v_pk_add_f32 v[218:219], v[218:219], v[220:221]
	v_add_f32_e32 v218, v218, v219
	s_nop 1
	v_add_f32_dpp v219, v218, v218 quad_perm:[1,0,3,2] row_mask:0xf bank_mask:0xf
	s_nop 1
	v_add_f32_dpp v218, v219, v219 quad_perm:[2,3,0,1] row_mask:0xf bank_mask:0xf
	v_fmamk_f32 v218, v218, 0x3c800000, v111
	v_rsq_f32_e32 v218, v218
	s_nop 0
	v_pk_mul_f32 v[200:201], v[200:201], v[218:219] op_sel_hi:[1,0]
	v_pk_mul_f32 v[202:203], v[202:203], v[218:219] op_sel_hi:[1,0]
	v_pk_mul_f32 v[204:205], v[204:205], v[218:219] op_sel_hi:[1,0]
	v_pk_mul_f32 v[206:207], v[206:207], v[218:219] op_sel_hi:[1,0]
	v_pk_mul_f32 v[208:209], v[208:209], v[218:219] op_sel_hi:[1,0]
	v_pk_mul_f32 v[210:211], v[210:211], v[218:219] op_sel_hi:[1,0]
	v_pk_mul_f32 v[212:213], v[212:213], v[218:219] op_sel_hi:[1,0]
	v_pk_mul_f32 v[214:215], v[214:215], v[218:219] op_sel_hi:[1,0]
	v_pk_fma_f32 v[200:201], v[200:201], v[152:153], v[168:169]
	v_pk_fma_f32 v[202:203], v[202:203], v[154:155], v[170:171]
	v_pk_fma_f32 v[204:205], v[204:205], v[156:157], v[172:173]
	v_pk_fma_f32 v[206:207], v[206:207], v[158:159], v[174:175]
	v_pk_fma_f32 v[208:209], v[208:209], v[160:161], v[176:177]
	v_pk_fma_f32 v[210:211], v[210:211], v[162:163], v[178:179]
	v_pk_fma_f32 v[212:213], v[212:213], v[164:165], v[180:181]
	v_pk_fma_f32 v[214:215], v[214:215], v[166:167], v[182:183]
	v_cvt_pk_bf16_f32 v224, v200, v201
	v_cvt_pk_bf16_f32 v225, v202, v203
	v_cvt_pk_bf16_f32 v226, v204, v205
	v_cvt_pk_bf16_f32 v227, v206, v207
	v_cvt_pk_bf16_f32 v228, v208, v209
	v_cvt_pk_bf16_f32 v229, v210, v211
	v_cvt_pk_bf16_f32 v230, v212, v213
	v_cvt_pk_bf16_f32 v231, v214, v215
	ds_write_b16 v117, v224 offset:17408
	ds_write_b16_d16_hi v117, v224 offset:17680
	ds_write_b16 v117, v225 offset:17952
	ds_write_b16_d16_hi v117, v225 offset:18224
	ds_write_b16 v117, v226 offset:18496
	ds_write_b16_d16_hi v117, v226 offset:18768
	ds_write_b16 v117, v227 offset:19040
	ds_write_b16_d16_hi v117, v227 offset:19312
	ds_write_b16 v117, v228 offset:19584
	ds_write_b16_d16_hi v117, v228 offset:19856
	ds_write_b16 v117, v229 offset:20128
	ds_write_b16_d16_hi v117, v229 offset:20400
	ds_write_b16 v117, v230 offset:20672
	ds_write_b16_d16_hi v117, v230 offset:20944
	ds_write_b16 v117, v231 offset:21216
	ds_write_b16_d16_hi v117, v231 offset:21488
	s_waitcnt lgkmcnt(0)
	s_barrier
	ds_read_b128 v[88:91], v118 offset:17408
	ds_read_b128 v[92:95], v118 offset:17440
	ds_read_b128 v[96:99], v118 offset:17472
	ds_read_b128 v[100:103], v118 offset:17504
	s_waitcnt lgkmcnt(3)
	v_mfma_f32_32x32x16_bf16 v[0:15], v[88:91], v[120:123], 0
	s_waitcnt lgkmcnt(2)
	v_mfma_f32_32x32x16_bf16 v[0:15], v[92:95], v[124:127], v[0:15]
	s_waitcnt lgkmcnt(1)
	v_mfma_f32_32x32x16_bf16 v[0:15], v[96:99], v[128:131], v[0:15]
	s_waitcnt lgkmcnt(0)
	v_mfma_f32_32x32x16_bf16 v[0:15], v[100:103], v[132:135], v[0:15]
	s_cmp_lt_u32 s20, 0x100
	s_cbranch_scc1 .Lp3r_halft1
	ds_read_b128 v[88:91], v118 offset:17536
	ds_read_b128 v[92:95], v118 offset:17568
	ds_read_b128 v[96:99], v118 offset:17600
	ds_read_b128 v[100:103], v118 offset:17632
	s_waitcnt lgkmcnt(3)
	v_mfma_f32_32x32x16_bf16 v[0:15], v[88:91], v[136:139], v[0:15]
	s_waitcnt lgkmcnt(2)
	v_mfma_f32_32x32x16_bf16 v[0:15], v[92:95], v[140:143], v[0:15]
	s_waitcnt lgkmcnt(1)
	v_mfma_f32_32x32x16_bf16 v[0:15], v[96:99], v[144:147], v[0:15]
	s_waitcnt lgkmcnt(0)
	v_mfma_f32_32x32x16_bf16 v[0:15], v[100:103], v[148:151], v[0:15]
; __device__ __forceinline__ unsigned pk2(float lo, float hi) { f32x2_t v = {lo, hi}; bf16x2_t b = __builtin_convertvector(v, bf16x2_t); return __builtin_bit_cast(unsigned, b); }
; __device__ __forceinline__ float bf_lo(unsigned u) { return __uint_as_float(u << 16); }
; __device__ __forceinline__ float bf_hi(unsigned u) { return __uint_as_float(u & 0xffff0000u); }
; __global__ void __launch_bounds__(512, 2) mega_fwd(Args a) {
;     ...
;             {
;                 float xv[16];
;                 xv[0] = bf_lo(r0.x); xv[1] = bf_hi(r0.x); xv[2] = bf_lo(r0.y); xv[3] = bf_hi(r0.y); xv[4] = bf_lo(r0.z); xv[5] = bf_hi(r0.z); xv[6] = bf_lo(r0.w); xv[7] = bf_hi(r0.w);
;                 xv[8] = bf_lo(r1.x); xv[9] = bf_hi(r1.x); xv[10] = bf_lo(r1.y); xv[11] = bf_hi(r1.y); xv[12] = bf_lo(r1.z); xv[13] = bf_hi(r1.z); xv[14] = bf_lo(r1.w); xv[15] = bf_hi(r1.w);
;                 float sm = 0.f;
; #pragma unroll
;                 for (int e = 0; e < 16; ++e) sm += xv[e];
;                 sm += __shfl_xor(sm, 1); sm += __shfl_xor(sm, 2);
;                 const float mu = sm * (1.0f / 64.0f); float q = 0.f;
; #pragma unroll
;                 for (int e = 0; e < 16; ++e) { xv[e] -= mu; q += xv[e] * xv[e]; }
;                 q += __shfl_xor(q, 1); q += __shfl_xor(q, 2);
;                 const float rstd = rsqrtf(q * (1.0f / 64.0f) + EPS);
; #pragma unroll
;                 for (int e = 0; e < 16; ++e) { const float y = xv[e] * rstd * lgv[e >> 2][e & 3] + lbv[e >> 2][e & 3]; VLT[(16 * qd + e) * VLP + jt] = (bf16_t)(pk2(y, 0.f) & 0xffffu); }
;             }
;     ...
;                 bf16_t* op = AO + (t0 + itok) * DM + 512 + h * 64 + 32 * dblk + 4 * hi;
; #pragma unroll
;                 for (int g = 0; g < 4; ++g) {
;                     u32x2 w; w.x = pk2(bf_lo(uu[g].x) * (acc[4 * g] + bsp), bf_hi(uu[g].x) * (acc[4 * g + 1] + bsp)); w.y = pk2(bf_lo(uu[g].y) * (acc[4 * g + 2] + bsp), bf_hi(uu[g].y) * (acc[4 * g + 3] + bsp));
;                     *(u32x2*)(op + 8 * g) = w;
;                 }
.Lp3r_halft1:
	s_waitcnt vmcnt(0)
	v_permlane32_swap_b32_e32 v48, v50
	v_permlane32_swap_b32_e32 v49, v51
	v_permlane32_swap_b32_e32 v52, v54
	v_permlane32_swap_b32_e32 v53, v55
	s_nop 0
	v_lshlrev_b32_e32 v200, 16, v48
	v_and_b32_e32 v201, s38, v48
	v_lshlrev_b32_e32 v202, 16, v49
	v_and_b32_e32 v203, s38, v49
	v_lshlrev_b32_e32 v204, 16, v52
	v_and_b32_e32 v205, s38, v52
	v_lshlrev_b32_e32 v206, 16, v53
	v_and_b32_e32 v207, s38, v53
	v_lshlrev_b32_e32 v208, 16, v50
	v_and_b32_e32 v209, s38, v50
	v_lshlrev_b32_e32 v210, 16, v51
	v_and_b32_e32 v211, s38, v51
	v_lshlrev_b32_e32 v212, 16, v54
	v_and_b32_e32 v213, s38, v54
	v_lshlrev_b32_e32 v214, 16, v55
	v_and_b32_e32 v215, s38, v55
	s_nop 7
	v_pk_add_f32 v[0:1], v[0:1], v[32:33] op_sel_hi:[1,0]
	v_pk_add_f32 v[2:3], v[2:3], v[32:33] op_sel_hi:[1,0]
	v_pk_add_f32 v[4:5], v[4:5], v[32:33] op_sel_hi:[1,0]
	v_pk_add_f32 v[6:7], v[6:7], v[32:33] op_sel_hi:[1,0]
	v_pk_add_f32 v[8:9], v[8:9], v[32:33] op_sel_hi:[1,0]
	v_pk_add_f32 v[10:11], v[10:11], v[32:33] op_sel_hi:[1,0]
	v_pk_add_f32 v[12:13], v[12:13], v[32:33] op_sel_hi:[1,0]
	v_pk_add_f32 v[14:15], v[14:15], v[32:33] op_sel_hi:[1,0]
	v_pk_mul_f32 v[0:1], v[0:1], v[200:201]
	v_pk_mul_f32 v[2:3], v[2:3], v[202:203]
	v_pk_mul_f32 v[4:5], v[4:5], v[204:205]
	v_pk_mul_f32 v[6:7], v[6:7], v[206:207]
	v_pk_mul_f32 v[8:9], v[8:9], v[208:209]
	v_pk_mul_f32 v[10:11], v[10:11], v[210:211]
	v_pk_mul_f32 v[12:13], v[12:13], v[212:213]
	v_pk_mul_f32 v[14:15], v[14:15], v[214:215]
	v_cvt_pk_bf16_f32 v224, v0, v1
	v_cvt_pk_bf16_f32 v225, v2, v3
	v_cvt_pk_bf16_f32 v228, v4, v5
	v_cvt_pk_bf16_f32 v229, v6, v7
	v_cvt_pk_bf16_f32 v226, v8, v9
	v_cvt_pk_bf16_f32 v227, v10, v11
	v_cvt_pk_bf16_f32 v230, v12, v13
	v_cvt_pk_bf16_f32 v231, v14, v15
	s_nop 1
	v_permlane32_swap_b32_e32 v224, v226
	v_permlane32_swap_b32_e32 v225, v227
	v_permlane32_swap_b32_e32 v228, v230
	v_permlane32_swap_b32_e32 v229, v231
	global_store_dwordx4 v234, v[224:227], s[48:49]
	global_store_dwordx4 v234, v[228:231], s[48:49] offset:16
	s_add_u32 s48, s48, 0x40000
	s_addc_u32 s49, s49, 0
	s_add_u32 s45, s45, 1
	s_cmp_lt_u32 s45, s18
	s_cbranch_scc0 .Lp3_done
.Lp3r_tail2:
	s_waitcnt vmcnt(3)
	v_lshlrev_b32_e32 v200, 16, v56
	v_and_b32_e32 v201, s38, v56
	v_lshlrev_b32_e32 v202, 16, v57
	v_and_b32_e32 v203, s38, v57
	v_lshlrev_b32_e32 v204, 16, v58
	v_and_b32_e32 v205, s38, v58
	v_lshlrev_b32_e32 v206, 16, v59
	v_and_b32_e32 v207, s38, v59
	s_waitcnt vmcnt(2)
	v_lshlrev_b32_e32 v208, 16, v60
	v_and_b32_e32 v209, s38, v60
	v_lshlrev_b32_e32 v210, 16, v61
	v_and_b32_e32 v211, s38, v61
	v_lshlrev_b32_e32 v212, 16, v62
	v_and_b32_e32 v213, s38, v62
	v_lshlrev_b32_e32 v214, 16, v63
	v_and_b32_e32 v215, s38, v63
	v_pk_add_f32 v[216:217], v[200:201], v[202:203]
	v_pk_add_f32 v[218:219], v[204:205], v[206:207]
	v_pk_add_f32 v[220:221], v[208:209], v[210:211]
	v_pk_add_f32 v[222:223], v[212:213], v[214:215]
	v_pk_add_f32 v[216:217], v[216:217], v[218:219]
	v_pk_add_f32 v[220:221], v[220:221], v[222:223]
	v_pk_add_f32 v[216:217], v[216:217], v[220:221]
	v_add_f32_e32 v216, v216, v217
	s_nop 1
	v_add_f32_dpp v217, v216, v216 quad_perm:[1,0,3,2] row_mask:0xf bank_mask:0xf
	s_nop 1
	v_add_f32_dpp v216, v217, v217 quad_perm:[2,3,0,1] row_mask:0xf bank_mask:0xf
	v_mul_f32_e32 v216, 0xbc800000, v216
	v_pk_add_f32 v[200:201], v[200:201], v[216:217] op_sel_hi:[1,0]
	v_pk_add_f32 v[202:203], v[202:203], v[216:217] op_sel_hi:[1,0]
	v_pk_add_f32 v[204:205], v[204:205], v[216:217] op_sel_hi:[1,0]
	v_pk_add_f32 v[206:207], v[206:207], v[216:217] op_sel_hi:[1,0]
	v_pk_add_f32 v[208:209], v[208:209], v[216:217] op_sel_hi:[1,0]
	v_pk_add_f32 v[210:211], v[210:211], v[216:217] op_sel_hi:[1,0]
	v_pk_add_f32 v[212:213], v[212:213], v[216:217] op_sel_hi:[1,0]
	v_pk_add_f32 v[214:215], v[214:215], v[216:217] op_sel_hi:[1,0]
	v_pk_mul_f32 v[218:219], v[200:201], v[200:201]
	v_pk_mul_f32 v[220:221], v[202:203], v[202:203]
	v_pk_fma_f32 v[218:219], v[204:205], v[204:205], v[218:219]
	v_pk_fma_f32 v[220:221], v[206:207], v[206:207], v[220:221]
	v_pk_fma_f32 v[218:219], v[208:209], v[208:209], v[218:219]
	v_pk_fma_f32 v[220:221], v[210:211], v[210:211], v[220:221]
	v_pk_fma_f32 v[218:219], v[212:213], v[212:213], v[218:219]
	v_pk_fma_f32 v[220:221], v[214:215], v[214:215], v[220:221]
	v_pk_add_f32 v[218:219], v[218:219], v[220:221]
	v_add_f32_e32 v218, v218, v219
	s_nop 1
	v_add_f32_dpp v219, v218, v218 quad_perm:[1,0,3,2] row_mask:0xf bank_mask:0xf
	s_nop 1
	v_add_f32_dpp v218, v219, v219 quad_perm:[2,3,0,1] row_mask:0xf bank_mask:0xf
	v_fmamk_f32 v218, v218, 0x3c800000, v111
	v_rsq_f32_e32 v218, v218
	s_nop 0
	v_pk_mul_f32 v[200:201], v[200:201], v[218:219] op_sel_hi:[1,0]
	v_pk_mul_f32 v[202:203], v[202:203], v[218:219] op_sel_hi:[1,0]
	v_pk_mul_f32 v[204:205], v[204:205], v[218:219] op_sel_hi:[1,0]
	v_pk_mul_f32 v[206:207], v[206:207], v[218:219] op_sel_hi:[1,0]
	v_pk_mul_f32 v[208:209], v[208:209], v[218:219] op_sel_hi:[1,0]
	v_pk_mul_f32 v[210:211], v[210:211], v[218:219] op_sel_hi:[1,0]
	v_pk_mul_f32 v[212:213], v[212:213], v[218:219] op_sel_hi:[1,0]
	v_pk_mul_f32 v[214:215], v[214:215], v[218:219] op_sel_hi:[1,0]
	v_pk_fma_f32 v[200:201], v[200:201], v[152:153], v[168:169]
	v_pk_fma_f32 v[202:203], v[202:203], v[154:155], v[170:171]
	v_pk_fma_f32 v[204:205], v[204:205], v[156:157], v[172:173]
	v_pk_fma_f32 v[206:207], v[206:207], v[158:159], v[174:175]
	v_pk_fma_f32 v[208:209], v[208:209], v[160:161], v[176:177]
	v_pk_fma_f32 v[210:211], v[210:211], v[162:163], v[178:179]
	v_pk_fma_f32 v[212:213], v[212:213], v[164:165], v[180:181]
	v_pk_fma_f32 v[214:215], v[214:215], v[166:167], v[182:183]
	v_cvt_pk_bf16_f32 v224, v200, v201
	v_cvt_pk_bf16_f32 v225, v202, v203
	v_cvt_pk_bf16_f32 v226, v204, v205
	v_cvt_pk_bf16_f32 v227, v206, v207
	v_cvt_pk_bf16_f32 v228, v208, v209
	v_cvt_pk_bf16_f32 v229, v210, v211
	v_cvt_pk_bf16_f32 v230, v212, v213
	v_cvt_pk_bf16_f32 v231, v214, v215
	ds_write_b16 v117, v224 offset:34816
	ds_write_b16_d16_hi v117, v224 offset:35088
	ds_write_b16 v117, v225 offset:35360
	ds_write_b16_d16_hi v117, v225 offset:35632
	ds_write_b16 v117, v226 offset:35904
	ds_write_b16_d16_hi v117, v226 offset:36176
	ds_write_b16 v117, v227 offset:36448
	ds_write_b16_d16_hi v117, v227 offset:36720
	ds_write_b16 v117, v228 offset:36992
	ds_write_b16_d16_hi v117, v228 offset:37264
	ds_write_b16 v117, v229 offset:37536
	ds_write_b16_d16_hi v117, v229 offset:37808
	ds_write_b16 v117, v230 offset:38080
	ds_write_b16_d16_hi v117, v230 offset:38352
	ds_write_b16 v117, v231 offset:38624
	ds_write_b16_d16_hi v117, v231 offset:38896
	s_waitcnt lgkmcnt(0)
	s_barrier
; #define LAS __attribute__((address_space(3)))
; __device__ __forceinline__ unsigned pk2(float lo, float hi) { f32x2_t v = {lo, hi}; bf16x2_t b = __builtin_convertvector(v, bf16x2_t); return __builtin_bit_cast(unsigned, b); }
; __device__ __forceinline__ float bf_lo(unsigned u) { return __uint_as_float(u << 16); }
; __device__ __forceinline__ float bf_hi(unsigned u) { return __uint_as_float(u & 0xffff0000u); }
; __global__ void __launch_bounds__(512, 2) mega_fwd(Args a) {
;     ...
;             {
;                 f32x16 acc;
; #pragma unroll
;                 for (int r = 0; r < 16; ++r) acc[r] = 0.f;
;                 const LAS bf16_t* vl = VLT + (32 * dblk + r32) * VLP + 8 * hi;
; #pragma unroll
;                 for (int s = 0; s < 8; ++s) if (s < 4 || iblk >= 2) {
;                     const bf16x8 vf = *(const LAS bf16x8*)(vl + 16 * s);
;                     acc = __builtin_amdgcn_mfma_f32_32x32x16_bf16(vf, wf[s], acc, 0, 0, 0);
;                 }
;                 bf16_t* op = AO + (t0 + itok) * DM + 512 + h * 64 + 32 * dblk + 4 * hi;
; #pragma unroll
;                 for (int g = 0; g < 4; ++g) {
;                     u32x2 w; w.x = pk2(bf_lo(uu[g].x) * (acc[4 * g] + bsp), bf_hi(uu[g].x) * (acc[4 * g + 1] + bsp)); w.y = pk2(bf_lo(uu[g].y) * (acc[4 * g + 2] + bsp), bf_hi(uu[g].y) * (acc[4 * g + 3] + bsp));
;                     *(u32x2*)(op + 8 * g) = w;
;                 }
	ds_read_b128 v[88:91], v118 offset:34816
	ds_read_b128 v[92:95], v118 offset:34848
	ds_read_b128 v[96:99], v118 offset:34880
	ds_read_b128 v[100:103], v118 offset:34912
	s_waitcnt lgkmcnt(3)
	v_mfma_f32_32x32x16_bf16 v[0:15], v[88:91], v[120:123], 0
	s_waitcnt lgkmcnt(2)
	v_mfma_f32_32x32x16_bf16 v[0:15], v[92:95], v[124:127], v[0:15]
	s_waitcnt lgkmcnt(1)
	v_mfma_f32_32x32x16_bf16 v[0:15], v[96:99], v[128:131], v[0:15]
	s_waitcnt lgkmcnt(0)
	v_mfma_f32_32x32x16_bf16 v[0:15], v[100:103], v[132:135], v[0:15]
	s_cmp_lt_u32 s20, 0x100
	s_cbranch_scc1 .Lp3r_halft2
	ds_read_b128 v[88:91], v118 offset:34944
	ds_read_b128 v[92:95], v118 offset:34976
	ds_read_b128 v[96:99], v118 offset:35008
	ds_read_b128 v[100:103], v118 offset:35040
	s_waitcnt lgkmcnt(3)
	v_mfma_f32_32x32x16_bf16 v[0:15], v[88:91], v[136:139], v[0:15]
	s_waitcnt lgkmcnt(2)
	v_mfma_f32_32x32x16_bf16 v[0:15], v[92:95], v[140:143], v[0:15]
	s_waitcnt lgkmcnt(1)
	v_mfma_f32_32x32x16_bf16 v[0:15], v[96:99], v[144:147], v[0:15]
	s_waitcnt lgkmcnt(0)
	v_mfma_f32_32x32x16_bf16 v[0:15], v[100:103], v[148:151], v[0:15]
.Lp3r_halft2:
	s_waitcnt vmcnt(0)
	v_permlane32_swap_b32_e32 v64, v66
	v_permlane32_swap_b32_e32 v65, v67
	v_permlane32_swap_b32_e32 v68, v70
	v_permlane32_swap_b32_e32 v69, v71
	s_nop 0
	v_lshlrev_b32_e32 v200, 16, v64
	v_and_b32_e32 v201, s38, v64
	v_lshlrev_b32_e32 v202, 16, v65
	v_and_b32_e32 v203, s38, v65
	v_lshlrev_b32_e32 v204, 16, v68
	v_and_b32_e32 v205, s38, v68
	v_lshlrev_b32_e32 v206, 16, v69
	v_and_b32_e32 v207, s38, v69
	v_lshlrev_b32_e32 v208, 16, v66
	v_and_b32_e32 v209, s38, v66
	v_lshlrev_b32_e32 v210, 16, v67
	v_and_b32_e32 v211, s38, v67
	v_lshlrev_b32_e32 v212, 16, v70
	v_and_b32_e32 v213, s38, v70
	v_lshlrev_b32_e32 v214, 16, v71
	v_and_b32_e32 v215, s38, v71
	s_nop 7
	v_pk_add_f32 v[0:1], v[0:1], v[32:33] op_sel_hi:[1,0]
	v_pk_add_f32 v[2:3], v[2:3], v[32:33] op_sel_hi:[1,0]
	v_pk_add_f32 v[4:5], v[4:5], v[32:33] op_sel_hi:[1,0]
	v_pk_add_f32 v[6:7], v[6:7], v[32:33] op_sel_hi:[1,0]
	v_pk_add_f32 v[8:9], v[8:9], v[32:33] op_sel_hi:[1,0]
	v_pk_add_f32 v[10:11], v[10:11], v[32:33] op_sel_hi:[1,0]
	v_pk_add_f32 v[12:13], v[12:13], v[32:33] op_sel_hi:[1,0]
	v_pk_add_f32 v[14:15], v[14:15], v[32:33] op_sel_hi:[1,0]
	v_pk_mul_f32 v[0:1], v[0:1], v[200:201]
	v_pk_mul_f32 v[2:3], v[2:3], v[202:203]
	v_pk_mul_f32 v[4:5], v[4:5], v[204:205]
	v_pk_mul_f32 v[6:7], v[6:7], v[206:207]
	v_pk_mul_f32 v[8:9], v[8:9], v[208:209]
	v_pk_mul_f32 v[10:11], v[10:11], v[210:211]
	v_pk_mul_f32 v[12:13], v[12:13], v[212:213]
	v_pk_mul_f32 v[14:15], v[14:15], v[214:215]
	v_cvt_pk_bf16_f32 v224, v0, v1
	v_cvt_pk_bf16_f32 v225, v2, v3
	v_cvt_pk_bf16_f32 v228, v4, v5
	v_cvt_pk_bf16_f32 v229, v6, v7
	v_cvt_pk_bf16_f32 v226, v8, v9
	v_cvt_pk_bf16_f32 v227, v10, v11
	v_cvt_pk_bf16_f32 v230, v12, v13
	v_cvt_pk_bf16_f32 v231, v14, v15
	s_nop 1
	v_permlane32_swap_b32_e32 v224, v226
	v_permlane32_swap_b32_e32 v225, v227
	v_permlane32_swap_b32_e32 v228, v230
	v_permlane32_swap_b32_e32 v229, v231
	global_store_dwordx4 v234, v[224:227], s[48:49]
	global_store_dwordx4 v234, v[228:231], s[48:49] offset:16
	s_add_u32 s48, s48, 0x40000
	s_addc_u32 s49, s49, 0
	s_add_u32 s45, s45, 1
	s_cmp_lt_u32 s45, s18
	s_cbranch_scc0 .Lp3_done
	s_branch .Lp3r_tail0
